# v19 + first wait of each unit's peeled first K-iteration relaxed to vmcnt(8+16) in P4/P5/P10/P12/P13/P15: it no longer waits for the 16 epilogue stores, only for the oldest staged half-tile
# baseline (speedup 1.0000x reference)
.LBB0_375:
	s_ashr_i32 s21, s20, 31
	s_lshl_b64 s[22:23], s[20:21], 21
	v_readlane_b32 s24, v251, 17
	v_readlane_b32 s25, v251, 18
	s_add_u32 s22, s24, s22
	s_addc_u32 s23, s25, s23
	s_and_b64 s[24:25], s[2:3], exec
	s_cselect_b32 s21, s23, s27
	s_cselect_b32 s80, s22, s26
	s_ashr_i32 s19, s18, 31
	s_lshl_b64 s[24:25], s[18:19], 21
	s_add_u32 s24, s42, s24
	s_addc_u32 s25, s43, s25
	s_and_b64 s[36:37], s[2:3], exec
	s_cselect_b32 s19, s25, s35
	s_cselect_b32 s81, s24, s34
	s_add_u32 s26, s26, 0x104000
	s_addc_u32 s27, s27, 0
	s_add_u32 s83, s34, 0x8000
	s_addc_u32 s86, s35, 0
	s_mov_b32 s87, -2
	ds_read_b128 v[130:133], v159
	ds_read_b128 v[162:165], v159 offset:1024
	ds_read_b128 v[166:169], v159 offset:2048
	ds_read_b128 v[170:173], v159 offset:3072
	ds_read_b128 v[174:177], v160
	ds_read_b128 v[178:181], v160 offset:1024
	ds_read_b128 v[182:185], v160 offset:2048
	ds_read_b128 v[186:189], v160 offset:3072
	s_add_u32 s34, s26, 0xfff04000
	s_addc_u32 s35, s27, -1
	s_cmp_eq_u32 s87, 60
	s_cselect_b32 s38, s80, s34
	s_cselect_b32 s39, s21, s35
	s_cselect_b32 s36, s81, s83
	s_cselect_b32 s37, s19, s86
	s_add_u32 s34, s38, 0x4000
	s_addc_u32 s35, s39, 0
	s_add_i32 m0, s46, 0xc000
	ds_read_b128 v[190:193], v161
	ds_read_b128 v[194:197], v161 offset:1024
	ds_read_b128 v[198:201], v161 offset:2048
	ds_read_b128 v[202:205], v161 offset:3072
	ds_read_b128 v[206:209], v161 offset:4096
	ds_read_b128 v[210:213], v161 offset:5120
	ds_read_b128 v[214:217], v161 offset:6144
	ds_read_b128 v[218:221], v161 offset:7168
	global_load_lds_dwordx4 v146, s[26:27]
	s_add_i32 m0, s46, 0xe000
	s_nop 0
	global_load_lds_dwordx4 v148, s[26:27]
	s_waitcnt vmcnt(24)
	s_waitcnt lgkmcnt(0)
	s_barrier
	s_waitcnt lgkmcnt(0)
	v_mfma_f32_16x16x32_bf16 v[62:65], v[130:133], v[190:193], 0
	v_mfma_f32_16x16x32_bf16 v[62:65], v[162:165], v[194:197], v[62:65]
	v_mfma_f32_16x16x32_bf16 v[58:61], v[166:169], v[190:193], 0
	v_mfma_f32_16x16x32_bf16 v[58:61], v[170:173], v[194:197], v[58:61]
	v_mfma_f32_16x16x32_bf16 v[54:57], v[130:133], v[198:201], 0
	v_mfma_f32_16x16x32_bf16 v[54:57], v[162:165], v[202:205], v[54:57]
	v_mfma_f32_16x16x32_bf16 v[50:53], v[166:169], v[198:201], 0
	v_mfma_f32_16x16x32_bf16 v[50:53], v[170:173], v[202:205], v[50:53]
	v_mfma_f32_16x16x32_bf16 v[46:49], v[130:133], v[206:209], 0
	v_mfma_f32_16x16x32_bf16 v[46:49], v[162:165], v[210:213], v[46:49]
	v_mfma_f32_16x16x32_bf16 v[42:45], v[166:169], v[206:209], 0
	v_mfma_f32_16x16x32_bf16 v[42:45], v[170:173], v[210:213], v[42:45]
	v_mfma_f32_16x16x32_bf16 v[38:41], v[130:133], v[214:217], 0
	v_mfma_f32_16x16x32_bf16 v[38:41], v[162:165], v[218:221], v[38:41]
	v_mfma_f32_16x16x32_bf16 v[34:37], v[166:169], v[214:217], 0
	v_mfma_f32_16x16x32_bf16 v[34:37], v[170:173], v[218:221], v[34:37]
	v_mfma_f32_16x16x32_bf16 v[126:129], v[174:177], v[190:193], 0
	v_mfma_f32_16x16x32_bf16 v[126:129], v[178:181], v[194:197], v[126:129]
	v_mfma_f32_16x16x32_bf16 v[122:125], v[182:185], v[190:193], 0
	v_mfma_f32_16x16x32_bf16 v[122:125], v[186:189], v[194:197], v[122:125]
	v_mfma_f32_16x16x32_bf16 v[118:121], v[174:177], v[198:201], 0
	v_mfma_f32_16x16x32_bf16 v[118:121], v[178:181], v[202:205], v[118:121]
	v_mfma_f32_16x16x32_bf16 v[114:117], v[182:185], v[198:201], 0
	v_mfma_f32_16x16x32_bf16 v[114:117], v[186:189], v[202:205], v[114:117]
	v_mfma_f32_16x16x32_bf16 v[110:113], v[174:177], v[206:209], 0
	v_mfma_f32_16x16x32_bf16 v[110:113], v[178:181], v[210:213], v[110:113]
	v_mfma_f32_16x16x32_bf16 v[106:109], v[182:185], v[206:209], 0
	v_mfma_f32_16x16x32_bf16 v[106:109], v[186:189], v[210:213], v[106:109]
	v_mfma_f32_16x16x32_bf16 v[102:105], v[174:177], v[214:217], 0
	v_mfma_f32_16x16x32_bf16 v[102:105], v[178:181], v[218:221], v[102:105]
	v_mfma_f32_16x16x32_bf16 v[98:101], v[182:185], v[214:217], 0
	v_mfma_f32_16x16x32_bf16 v[98:101], v[186:189], v[218:221], v[98:101]
	s_barrier
	s_add_i32 s88, s66, s41
	s_mov_b32 m0, s88
	ds_read_b128 v[190:193], v161 offset:16384
	ds_read_b128 v[194:197], v161 offset:17408
	ds_read_b128 v[198:201], v161 offset:18432
	ds_read_b128 v[202:205], v161 offset:19456
	ds_read_b128 v[206:209], v161 offset:20480
	ds_read_b128 v[210:213], v161 offset:21504
	ds_read_b128 v[214:217], v161 offset:22528
	ds_read_b128 v[218:221], v161 offset:23552
	global_load_lds_dwordx4 v138, s[36:37]
	s_add_i32 m0, s88, 0x2000
	s_add_u32 s88, s36, 0x100000
	s_addc_u32 s89, s37, 0
	s_add_i32 vcc_lo, s67, s41
	global_load_lds_dwordx4 v134, s[36:37]
	s_mov_b32 m0, vcc_lo
	s_nop 0
	global_load_lds_dwordx4 v138, s[88:89]
	s_add_i32 m0, vcc_lo, 0x2000
	s_nop 0
	global_load_lds_dwordx4 v134, s[88:89]
	s_mov_b32 m0, s46
	s_nop 0
	global_load_lds_dwordx4 v140, s[38:39]
	s_mov_b32 m0, s47
	s_nop 0
	global_load_lds_dwordx4 v136, s[38:39]
	s_waitcnt vmcnt(8)
	s_waitcnt lgkmcnt(0)
	s_barrier
	s_waitcnt lgkmcnt(0)
	v_mfma_f32_16x16x32_bf16 v[30:33], v[130:133], v[190:193], 0
	v_mfma_f32_16x16x32_bf16 v[30:33], v[162:165], v[194:197], v[30:33]
	v_mfma_f32_16x16x32_bf16 v[26:29], v[166:169], v[190:193], 0
	v_mfma_f32_16x16x32_bf16 v[26:29], v[170:173], v[194:197], v[26:29]
	v_mfma_f32_16x16x32_bf16 v[22:25], v[130:133], v[198:201], 0
	v_mfma_f32_16x16x32_bf16 v[22:25], v[162:165], v[202:205], v[22:25]
	v_mfma_f32_16x16x32_bf16 v[18:21], v[166:169], v[198:201], 0
	v_mfma_f32_16x16x32_bf16 v[18:21], v[170:173], v[202:205], v[18:21]
	v_mfma_f32_16x16x32_bf16 v[14:17], v[130:133], v[206:209], 0
	v_mfma_f32_16x16x32_bf16 v[14:17], v[162:165], v[210:213], v[14:17]
	v_mfma_f32_16x16x32_bf16 v[10:13], v[166:169], v[206:209], 0
	v_mfma_f32_16x16x32_bf16 v[10:13], v[170:173], v[210:213], v[10:13]
	v_mfma_f32_16x16x32_bf16 v[6:9], v[130:133], v[214:217], 0
	v_mfma_f32_16x16x32_bf16 v[6:9], v[162:165], v[218:221], v[6:9]
	v_mfma_f32_16x16x32_bf16 v[2:5], v[166:169], v[214:217], 0
	v_mfma_f32_16x16x32_bf16 v[2:5], v[170:173], v[218:221], v[2:5]
	v_mfma_f32_16x16x32_bf16 v[94:97], v[174:177], v[190:193], 0
	v_mfma_f32_16x16x32_bf16 v[94:97], v[178:181], v[194:197], v[94:97]
	v_mfma_f32_16x16x32_bf16 v[90:93], v[182:185], v[190:193], 0
	v_mfma_f32_16x16x32_bf16 v[90:93], v[186:189], v[194:197], v[90:93]
	v_mfma_f32_16x16x32_bf16 v[86:89], v[174:177], v[198:201], 0
	v_mfma_f32_16x16x32_bf16 v[86:89], v[178:181], v[202:205], v[86:89]
	v_mfma_f32_16x16x32_bf16 v[82:85], v[182:185], v[198:201], 0
	v_mfma_f32_16x16x32_bf16 v[82:85], v[186:189], v[202:205], v[82:85]
	v_mfma_f32_16x16x32_bf16 v[78:81], v[174:177], v[206:209], 0
	v_mfma_f32_16x16x32_bf16 v[78:81], v[178:181], v[210:213], v[78:81]
	v_mfma_f32_16x16x32_bf16 v[74:77], v[182:185], v[206:209], 0
	v_mfma_f32_16x16x32_bf16 v[74:77], v[186:189], v[210:213], v[74:77]
	v_mfma_f32_16x16x32_bf16 v[70:73], v[174:177], v[214:217], 0
	v_mfma_f32_16x16x32_bf16 v[70:73], v[178:181], v[218:221], v[70:73]
	v_mfma_f32_16x16x32_bf16 v[66:69], v[182:185], v[214:217], 0
	v_mfma_f32_16x16x32_bf16 v[66:69], v[186:189], v[218:221], v[66:69]
	s_barrier
	s_add_i32 s88, 0, 0x18000
	v_add_u32_e32 v154, s88, v157
	s_add_i32 s89, 0, 0x1c000
	ds_read_b128 v[130:133], v154
	ds_read_b128 v[162:165], v154 offset:1024
	ds_read_b128 v[166:169], v154 offset:2048
	ds_read_b128 v[170:173], v154 offset:3072
	v_add_u32_e32 v154, s89, v157
	ds_read_b128 v[174:177], v154
	ds_read_b128 v[178:181], v154 offset:1024
	ds_read_b128 v[182:185], v154 offset:2048
	ds_read_b128 v[186:189], v154 offset:3072
	s_add_u32 s38, s38, 0x100000
	s_addc_u32 s39, s39, 0
	s_mov_b32 m0, s58
	ds_read_b128 v[190:193], v161 offset:32768
	ds_read_b128 v[194:197], v161 offset:33792
	ds_read_b128 v[198:201], v161 offset:34816
	ds_read_b128 v[202:205], v161 offset:35840
	ds_read_b128 v[206:209], v161 offset:36864
	ds_read_b128 v[210:213], v161 offset:37888
	ds_read_b128 v[214:217], v161 offset:38912
	ds_read_b128 v[218:221], v161 offset:39936
	global_load_lds_dwordx4 v140, s[38:39]
	s_mov_b32 m0, s59
	s_nop 0
	global_load_lds_dwordx4 v136, s[38:39]
	s_waitcnt vmcnt(8)
	s_waitcnt lgkmcnt(0)
	s_barrier
	s_waitcnt lgkmcnt(0)
	v_mfma_f32_16x16x32_bf16 v[62:65], v[130:133], v[190:193], v[62:65]
	v_mfma_f32_16x16x32_bf16 v[62:65], v[162:165], v[194:197], v[62:65]
	v_mfma_f32_16x16x32_bf16 v[58:61], v[166:169], v[190:193], v[58:61]
	v_mfma_f32_16x16x32_bf16 v[58:61], v[170:173], v[194:197], v[58:61]
	v_mfma_f32_16x16x32_bf16 v[54:57], v[130:133], v[198:201], v[54:57]
	v_mfma_f32_16x16x32_bf16 v[54:57], v[162:165], v[202:205], v[54:57]
	v_mfma_f32_16x16x32_bf16 v[50:53], v[166:169], v[198:201], v[50:53]
	v_mfma_f32_16x16x32_bf16 v[50:53], v[170:173], v[202:205], v[50:53]
	v_mfma_f32_16x16x32_bf16 v[46:49], v[130:133], v[206:209], v[46:49]
	v_mfma_f32_16x16x32_bf16 v[46:49], v[162:165], v[210:213], v[46:49]
	v_mfma_f32_16x16x32_bf16 v[42:45], v[166:169], v[206:209], v[42:45]
	v_mfma_f32_16x16x32_bf16 v[42:45], v[170:173], v[210:213], v[42:45]
	v_mfma_f32_16x16x32_bf16 v[38:41], v[130:133], v[214:217], v[38:41]
	v_mfma_f32_16x16x32_bf16 v[38:41], v[162:165], v[218:221], v[38:41]
	v_mfma_f32_16x16x32_bf16 v[34:37], v[166:169], v[214:217], v[34:37]
	v_mfma_f32_16x16x32_bf16 v[34:37], v[170:173], v[218:221], v[34:37]
	v_mfma_f32_16x16x32_bf16 v[126:129], v[174:177], v[190:193], v[126:129]
	v_mfma_f32_16x16x32_bf16 v[126:129], v[178:181], v[194:197], v[126:129]
	v_mfma_f32_16x16x32_bf16 v[122:125], v[182:185], v[190:193], v[122:125]
	v_mfma_f32_16x16x32_bf16 v[122:125], v[186:189], v[194:197], v[122:125]
	v_mfma_f32_16x16x32_bf16 v[118:121], v[174:177], v[198:201], v[118:121]
	v_mfma_f32_16x16x32_bf16 v[118:121], v[178:181], v[202:205], v[118:121]
	v_mfma_f32_16x16x32_bf16 v[114:117], v[182:185], v[198:201], v[114:117]
	v_mfma_f32_16x16x32_bf16 v[114:117], v[186:189], v[202:205], v[114:117]
	v_mfma_f32_16x16x32_bf16 v[110:113], v[174:177], v[206:209], v[110:113]
	v_mfma_f32_16x16x32_bf16 v[110:113], v[178:181], v[210:213], v[110:113]
	v_mfma_f32_16x16x32_bf16 v[106:109], v[182:185], v[206:209], v[106:109]
	v_mfma_f32_16x16x32_bf16 v[106:109], v[186:189], v[210:213], v[106:109]
	v_mfma_f32_16x16x32_bf16 v[102:105], v[174:177], v[214:217], v[102:105]
	v_mfma_f32_16x16x32_bf16 v[102:105], v[178:181], v[218:221], v[102:105]
	v_mfma_f32_16x16x32_bf16 v[98:101], v[182:185], v[214:217], v[98:101]
	v_mfma_f32_16x16x32_bf16 v[98:101], v[186:189], v[218:221], v[98:101]
	s_barrier
	s_add_u32 s38, s36, 0x4000
	s_addc_u32 s39, s37, 0
	s_add_i32 s88, s88, s41
	s_mov_b32 m0, s88
	ds_read_b128 v[190:193], v161 offset:49152
	ds_read_b128 v[194:197], v161 offset:50176
	ds_read_b128 v[198:201], v161 offset:51200
	ds_read_b128 v[202:205], v161 offset:52224
	ds_read_b128 v[206:209], v161 offset:53248
	ds_read_b128 v[210:213], v161 offset:54272
	ds_read_b128 v[214:217], v161 offset:55296
	ds_read_b128 v[218:221], v161 offset:56320
	global_load_lds_dwordx4 v138, s[38:39]
	s_add_i32 m0, s88, 0x2000
	s_add_u32 s36, s36, 0x104000
	s_addc_u32 s37, s37, 0
	global_load_lds_dwordx4 v134, s[38:39]
	s_add_i32 s38, s89, s41
	s_mov_b32 m0, s38
	s_nop 0
	global_load_lds_dwordx4 v138, s[36:37]
	s_add_i32 m0, s38, 0x2000
	s_nop 0
	global_load_lds_dwordx4 v134, s[36:37]
	s_mov_b32 m0, s64
	s_nop 0
	global_load_lds_dwordx4 v140, s[34:35]
	s_mov_b32 m0, s65
	s_nop 0
	global_load_lds_dwordx4 v136, s[34:35]
	s_waitcnt vmcnt(8)
	s_waitcnt lgkmcnt(0)
	s_barrier
	s_waitcnt lgkmcnt(0)
	v_mfma_f32_16x16x32_bf16 v[30:33], v[130:133], v[190:193], v[30:33]
	v_mfma_f32_16x16x32_bf16 v[30:33], v[162:165], v[194:197], v[30:33]
	v_mfma_f32_16x16x32_bf16 v[26:29], v[166:169], v[190:193], v[26:29]
	v_mfma_f32_16x16x32_bf16 v[26:29], v[170:173], v[194:197], v[26:29]
	v_mfma_f32_16x16x32_bf16 v[22:25], v[130:133], v[198:201], v[22:25]
	v_mfma_f32_16x16x32_bf16 v[22:25], v[162:165], v[202:205], v[22:25]
	v_mfma_f32_16x16x32_bf16 v[18:21], v[166:169], v[198:201], v[18:21]
	v_mfma_f32_16x16x32_bf16 v[18:21], v[170:173], v[202:205], v[18:21]
	v_mfma_f32_16x16x32_bf16 v[14:17], v[130:133], v[206:209], v[14:17]
	v_mfma_f32_16x16x32_bf16 v[14:17], v[162:165], v[210:213], v[14:17]
	v_mfma_f32_16x16x32_bf16 v[10:13], v[166:169], v[206:209], v[10:13]
	v_mfma_f32_16x16x32_bf16 v[10:13], v[170:173], v[210:213], v[10:13]
	v_mfma_f32_16x16x32_bf16 v[6:9], v[130:133], v[214:217], v[6:9]
	v_mfma_f32_16x16x32_bf16 v[6:9], v[162:165], v[218:221], v[6:9]
	v_mfma_f32_16x16x32_bf16 v[2:5], v[166:169], v[214:217], v[2:5]
	v_mfma_f32_16x16x32_bf16 v[2:5], v[170:173], v[218:221], v[2:5]
	v_mfma_f32_16x16x32_bf16 v[94:97], v[174:177], v[190:193], v[94:97]
	v_mfma_f32_16x16x32_bf16 v[94:97], v[178:181], v[194:197], v[94:97]
	v_mfma_f32_16x16x32_bf16 v[90:93], v[182:185], v[190:193], v[90:93]
	v_mfma_f32_16x16x32_bf16 v[90:93], v[186:189], v[194:197], v[90:93]
	v_mfma_f32_16x16x32_bf16 v[86:89], v[174:177], v[198:201], v[86:89]
	v_mfma_f32_16x16x32_bf16 v[86:89], v[178:181], v[202:205], v[86:89]
	v_mfma_f32_16x16x32_bf16 v[82:85], v[182:185], v[198:201], v[82:85]
	v_mfma_f32_16x16x32_bf16 v[82:85], v[186:189], v[202:205], v[82:85]
	v_mfma_f32_16x16x32_bf16 v[78:81], v[174:177], v[206:209], v[78:81]
	v_mfma_f32_16x16x32_bf16 v[78:81], v[178:181], v[210:213], v[78:81]
	v_mfma_f32_16x16x32_bf16 v[74:77], v[182:185], v[206:209], v[74:77]
	v_mfma_f32_16x16x32_bf16 v[74:77], v[186:189], v[210:213], v[74:77]
	v_mfma_f32_16x16x32_bf16 v[70:73], v[174:177], v[214:217], v[70:73]
	v_mfma_f32_16x16x32_bf16 v[70:73], v[178:181], v[218:221], v[70:73]
	v_mfma_f32_16x16x32_bf16 v[66:69], v[182:185], v[214:217], v[66:69]
	v_mfma_f32_16x16x32_bf16 v[66:69], v[186:189], v[218:221], v[66:69]
	s_barrier
	s_add_i32 s87, s87, 2
	s_add_u32 s26, s26, 0x8000
	s_addc_u32 s27, s27, 0
	s_add_u32 s83, s83, 0x8000
	s_addc_u32 s86, s86, 0
	s_cmp_gt_u32 s87, 61

.LBB0_535:
	s_ashr_i32 s21, s20, 31
	s_lshl_b64 s[22:23], s[20:21], 21
	v_readlane_b32 s24, v251, 17
	v_readlane_b32 s25, v251, 18
	s_add_u32 s22, s24, s22
	s_addc_u32 s23, s25, s23
	s_and_b64 s[24:25], s[2:3], exec
	s_cselect_b32 s21, s23, s27
	s_cselect_b32 s74, s22, s26
	s_ashr_i32 s19, s18, 31
	s_lshl_b64 s[24:25], s[18:19], 21
	s_add_u32 s24, s39, s24
	s_addc_u32 s25, s40, s25
	s_and_b64 s[34:35], s[2:3], exec
	s_cselect_b32 s19, s25, s31
	s_cselect_b32 s75, s24, s30
	s_add_u32 s26, s26, 0x104000
	s_addc_u32 s27, s27, 0
	s_add_u32 s78, s30, 0x8000
	s_addc_u32 s79, s31, 0
	s_mov_b32 s80, -2
	ds_read_b128 v[130:133], v159
	ds_read_b128 v[162:165], v159 offset:1024
	ds_read_b128 v[166:169], v159 offset:2048
	ds_read_b128 v[170:173], v159 offset:3072
	ds_read_b128 v[174:177], v160
	ds_read_b128 v[178:181], v160 offset:1024
	ds_read_b128 v[182:185], v160 offset:2048
	ds_read_b128 v[186:189], v160 offset:3072
	s_add_u32 s30, s26, 0xfff04000
	s_addc_u32 s31, s27, -1
	s_cmp_eq_u32 s80, 60
	s_cselect_b32 s36, s74, s30
	s_cselect_b32 s37, s21, s31
	s_cselect_b32 s34, s75, s78
	s_cselect_b32 s35, s19, s79
	s_add_u32 s30, s36, 0x4000
	s_addc_u32 s31, s37, 0
	s_add_i32 m0, s42, 0xc000
	ds_read_b128 v[190:193], v161
	ds_read_b128 v[194:197], v161 offset:1024
	ds_read_b128 v[198:201], v161 offset:2048
	ds_read_b128 v[202:205], v161 offset:3072
	ds_read_b128 v[206:209], v161 offset:4096
	ds_read_b128 v[210:213], v161 offset:5120
	ds_read_b128 v[214:217], v161 offset:6144
	ds_read_b128 v[218:221], v161 offset:7168
	global_load_lds_dwordx4 v146, s[26:27]
	s_add_i32 m0, s42, 0xe000
	s_nop 0
	global_load_lds_dwordx4 v148, s[26:27]
	s_waitcnt vmcnt(24)
	s_waitcnt lgkmcnt(0)
	s_barrier
	s_waitcnt lgkmcnt(0)
	v_mfma_f32_16x16x32_bf16 v[62:65], v[130:133], v[190:193], 0
	v_mfma_f32_16x16x32_bf16 v[62:65], v[162:165], v[194:197], v[62:65]
	v_mfma_f32_16x16x32_bf16 v[58:61], v[166:169], v[190:193], 0
	v_mfma_f32_16x16x32_bf16 v[58:61], v[170:173], v[194:197], v[58:61]
	v_mfma_f32_16x16x32_bf16 v[54:57], v[130:133], v[198:201], 0
	v_mfma_f32_16x16x32_bf16 v[54:57], v[162:165], v[202:205], v[54:57]
	v_mfma_f32_16x16x32_bf16 v[50:53], v[166:169], v[198:201], 0
	v_mfma_f32_16x16x32_bf16 v[50:53], v[170:173], v[202:205], v[50:53]
	v_mfma_f32_16x16x32_bf16 v[46:49], v[130:133], v[206:209], 0
	v_mfma_f32_16x16x32_bf16 v[46:49], v[162:165], v[210:213], v[46:49]
	v_mfma_f32_16x16x32_bf16 v[42:45], v[166:169], v[206:209], 0
	v_mfma_f32_16x16x32_bf16 v[42:45], v[170:173], v[210:213], v[42:45]
	v_mfma_f32_16x16x32_bf16 v[38:41], v[130:133], v[214:217], 0
	v_mfma_f32_16x16x32_bf16 v[38:41], v[162:165], v[218:221], v[38:41]
	v_mfma_f32_16x16x32_bf16 v[34:37], v[166:169], v[214:217], 0
	v_mfma_f32_16x16x32_bf16 v[34:37], v[170:173], v[218:221], v[34:37]
	v_mfma_f32_16x16x32_bf16 v[126:129], v[174:177], v[190:193], 0
	v_mfma_f32_16x16x32_bf16 v[126:129], v[178:181], v[194:197], v[126:129]
	v_mfma_f32_16x16x32_bf16 v[122:125], v[182:185], v[190:193], 0
	v_mfma_f32_16x16x32_bf16 v[122:125], v[186:189], v[194:197], v[122:125]
	v_mfma_f32_16x16x32_bf16 v[118:121], v[174:177], v[198:201], 0
	v_mfma_f32_16x16x32_bf16 v[118:121], v[178:181], v[202:205], v[118:121]
	v_mfma_f32_16x16x32_bf16 v[114:117], v[182:185], v[198:201], 0
	v_mfma_f32_16x16x32_bf16 v[114:117], v[186:189], v[202:205], v[114:117]
	v_mfma_f32_16x16x32_bf16 v[110:113], v[174:177], v[206:209], 0
	v_mfma_f32_16x16x32_bf16 v[110:113], v[178:181], v[210:213], v[110:113]
	v_mfma_f32_16x16x32_bf16 v[106:109], v[182:185], v[206:209], 0
	v_mfma_f32_16x16x32_bf16 v[106:109], v[186:189], v[210:213], v[106:109]
	v_mfma_f32_16x16x32_bf16 v[102:105], v[174:177], v[214:217], 0
	v_mfma_f32_16x16x32_bf16 v[102:105], v[178:181], v[218:221], v[102:105]
	v_mfma_f32_16x16x32_bf16 v[98:101], v[182:185], v[214:217], 0
	v_mfma_f32_16x16x32_bf16 v[98:101], v[186:189], v[218:221], v[98:101]
	s_barrier
	s_add_i32 s81, s62, s38
	s_mov_b32 m0, s81
	ds_read_b128 v[190:193], v161 offset:16384
	ds_read_b128 v[194:197], v161 offset:17408
	ds_read_b128 v[198:201], v161 offset:18432
	ds_read_b128 v[202:205], v161 offset:19456
	ds_read_b128 v[206:209], v161 offset:20480
	ds_read_b128 v[210:213], v161 offset:21504
	ds_read_b128 v[214:217], v161 offset:22528
	ds_read_b128 v[218:221], v161 offset:23552
	global_load_lds_dwordx4 v138, s[34:35]
	s_add_i32 m0, s81, 0x2000
	s_add_u32 s86, s34, 0x100000
	s_addc_u32 s87, s35, 0
	s_add_i32 s81, s63, s38
	global_load_lds_dwordx4 v134, s[34:35]
	s_mov_b32 m0, s81
	s_nop 0
	global_load_lds_dwordx4 v138, s[86:87]
	s_add_i32 m0, s81, 0x2000
	s_nop 0
	global_load_lds_dwordx4 v134, s[86:87]
	s_mov_b32 m0, s42
	s_nop 0
	global_load_lds_dwordx4 v140, s[36:37]
	s_mov_b32 m0, s43
	s_nop 0
	global_load_lds_dwordx4 v136, s[36:37]
	s_waitcnt vmcnt(8)
	s_waitcnt lgkmcnt(0)
	s_barrier
	s_waitcnt lgkmcnt(0)
	v_mfma_f32_16x16x32_bf16 v[30:33], v[130:133], v[190:193], 0
	v_mfma_f32_16x16x32_bf16 v[30:33], v[162:165], v[194:197], v[30:33]
	v_mfma_f32_16x16x32_bf16 v[26:29], v[166:169], v[190:193], 0
	v_mfma_f32_16x16x32_bf16 v[26:29], v[170:173], v[194:197], v[26:29]
	v_mfma_f32_16x16x32_bf16 v[22:25], v[130:133], v[198:201], 0
	v_mfma_f32_16x16x32_bf16 v[22:25], v[162:165], v[202:205], v[22:25]
	v_mfma_f32_16x16x32_bf16 v[18:21], v[166:169], v[198:201], 0
	v_mfma_f32_16x16x32_bf16 v[18:21], v[170:173], v[202:205], v[18:21]
	v_mfma_f32_16x16x32_bf16 v[14:17], v[130:133], v[206:209], 0
	v_mfma_f32_16x16x32_bf16 v[14:17], v[162:165], v[210:213], v[14:17]
	v_mfma_f32_16x16x32_bf16 v[10:13], v[166:169], v[206:209], 0
	v_mfma_f32_16x16x32_bf16 v[10:13], v[170:173], v[210:213], v[10:13]
	v_mfma_f32_16x16x32_bf16 v[6:9], v[130:133], v[214:217], 0
	v_mfma_f32_16x16x32_bf16 v[6:9], v[162:165], v[218:221], v[6:9]
	v_mfma_f32_16x16x32_bf16 v[2:5], v[166:169], v[214:217], 0
	v_mfma_f32_16x16x32_bf16 v[2:5], v[170:173], v[218:221], v[2:5]
	v_mfma_f32_16x16x32_bf16 v[94:97], v[174:177], v[190:193], 0
	v_mfma_f32_16x16x32_bf16 v[94:97], v[178:181], v[194:197], v[94:97]
	v_mfma_f32_16x16x32_bf16 v[90:93], v[182:185], v[190:193], 0
	v_mfma_f32_16x16x32_bf16 v[90:93], v[186:189], v[194:197], v[90:93]
	v_mfma_f32_16x16x32_bf16 v[86:89], v[174:177], v[198:201], 0
	v_mfma_f32_16x16x32_bf16 v[86:89], v[178:181], v[202:205], v[86:89]
	v_mfma_f32_16x16x32_bf16 v[82:85], v[182:185], v[198:201], 0
	v_mfma_f32_16x16x32_bf16 v[82:85], v[186:189], v[202:205], v[82:85]
	v_mfma_f32_16x16x32_bf16 v[78:81], v[174:177], v[206:209], 0
	v_mfma_f32_16x16x32_bf16 v[78:81], v[178:181], v[210:213], v[78:81]
	v_mfma_f32_16x16x32_bf16 v[74:77], v[182:185], v[206:209], 0
	v_mfma_f32_16x16x32_bf16 v[74:77], v[186:189], v[210:213], v[74:77]
	v_mfma_f32_16x16x32_bf16 v[70:73], v[174:177], v[214:217], 0
	v_mfma_f32_16x16x32_bf16 v[70:73], v[178:181], v[218:221], v[70:73]
	v_mfma_f32_16x16x32_bf16 v[66:69], v[182:185], v[214:217], 0
	v_mfma_f32_16x16x32_bf16 v[66:69], v[186:189], v[218:221], v[66:69]
	s_barrier
	s_add_i32 s81, 0, 0x18000
	v_add_u32_e32 v154, s81, v157
	s_add_i32 s83, 0, 0x1c000
	ds_read_b128 v[130:133], v154
	ds_read_b128 v[162:165], v154 offset:1024
	ds_read_b128 v[166:169], v154 offset:2048
	ds_read_b128 v[170:173], v154 offset:3072
	v_add_u32_e32 v154, s83, v157
	ds_read_b128 v[174:177], v154
	ds_read_b128 v[178:181], v154 offset:1024
	ds_read_b128 v[182:185], v154 offset:2048
	ds_read_b128 v[186:189], v154 offset:3072
	s_add_u32 s36, s36, 0x100000
	s_addc_u32 s37, s37, 0
	s_mov_b32 m0, s46
	ds_read_b128 v[190:193], v161 offset:32768
	ds_read_b128 v[194:197], v161 offset:33792
	ds_read_b128 v[198:201], v161 offset:34816
	ds_read_b128 v[202:205], v161 offset:35840
	ds_read_b128 v[206:209], v161 offset:36864
	ds_read_b128 v[210:213], v161 offset:37888
	ds_read_b128 v[214:217], v161 offset:38912
	ds_read_b128 v[218:221], v161 offset:39936
	global_load_lds_dwordx4 v140, s[36:37]
	s_mov_b32 m0, s47
	s_nop 0
	global_load_lds_dwordx4 v136, s[36:37]
	s_waitcnt vmcnt(8)
	s_waitcnt lgkmcnt(0)
	s_barrier
	s_waitcnt lgkmcnt(0)
	v_mfma_f32_16x16x32_bf16 v[62:65], v[130:133], v[190:193], v[62:65]
	v_mfma_f32_16x16x32_bf16 v[62:65], v[162:165], v[194:197], v[62:65]
	v_mfma_f32_16x16x32_bf16 v[58:61], v[166:169], v[190:193], v[58:61]
	v_mfma_f32_16x16x32_bf16 v[58:61], v[170:173], v[194:197], v[58:61]
	v_mfma_f32_16x16x32_bf16 v[54:57], v[130:133], v[198:201], v[54:57]
	v_mfma_f32_16x16x32_bf16 v[54:57], v[162:165], v[202:205], v[54:57]
	v_mfma_f32_16x16x32_bf16 v[50:53], v[166:169], v[198:201], v[50:53]
	v_mfma_f32_16x16x32_bf16 v[50:53], v[170:173], v[202:205], v[50:53]
	v_mfma_f32_16x16x32_bf16 v[46:49], v[130:133], v[206:209], v[46:49]
	v_mfma_f32_16x16x32_bf16 v[46:49], v[162:165], v[210:213], v[46:49]
	v_mfma_f32_16x16x32_bf16 v[42:45], v[166:169], v[206:209], v[42:45]
	v_mfma_f32_16x16x32_bf16 v[42:45], v[170:173], v[210:213], v[42:45]
	v_mfma_f32_16x16x32_bf16 v[38:41], v[130:133], v[214:217], v[38:41]
	v_mfma_f32_16x16x32_bf16 v[38:41], v[162:165], v[218:221], v[38:41]
	v_mfma_f32_16x16x32_bf16 v[34:37], v[166:169], v[214:217], v[34:37]
	v_mfma_f32_16x16x32_bf16 v[34:37], v[170:173], v[218:221], v[34:37]
	v_mfma_f32_16x16x32_bf16 v[126:129], v[174:177], v[190:193], v[126:129]
	v_mfma_f32_16x16x32_bf16 v[126:129], v[178:181], v[194:197], v[126:129]
	v_mfma_f32_16x16x32_bf16 v[122:125], v[182:185], v[190:193], v[122:125]
	v_mfma_f32_16x16x32_bf16 v[122:125], v[186:189], v[194:197], v[122:125]
	v_mfma_f32_16x16x32_bf16 v[118:121], v[174:177], v[198:201], v[118:121]
	v_mfma_f32_16x16x32_bf16 v[118:121], v[178:181], v[202:205], v[118:121]
	v_mfma_f32_16x16x32_bf16 v[114:117], v[182:185], v[198:201], v[114:117]
	v_mfma_f32_16x16x32_bf16 v[114:117], v[186:189], v[202:205], v[114:117]
	v_mfma_f32_16x16x32_bf16 v[110:113], v[174:177], v[206:209], v[110:113]
	v_mfma_f32_16x16x32_bf16 v[110:113], v[178:181], v[210:213], v[110:113]
	v_mfma_f32_16x16x32_bf16 v[106:109], v[182:185], v[206:209], v[106:109]
	v_mfma_f32_16x16x32_bf16 v[106:109], v[186:189], v[210:213], v[106:109]
	v_mfma_f32_16x16x32_bf16 v[102:105], v[174:177], v[214:217], v[102:105]
	v_mfma_f32_16x16x32_bf16 v[102:105], v[178:181], v[218:221], v[102:105]
	v_mfma_f32_16x16x32_bf16 v[98:101], v[182:185], v[214:217], v[98:101]
	v_mfma_f32_16x16x32_bf16 v[98:101], v[186:189], v[218:221], v[98:101]
	s_barrier
	s_add_u32 s36, s34, 0x4000
	s_addc_u32 s37, s35, 0
	s_add_i32 s81, s81, s38
	s_mov_b32 m0, s81
	ds_read_b128 v[190:193], v161 offset:49152
	ds_read_b128 v[194:197], v161 offset:50176
	ds_read_b128 v[198:201], v161 offset:51200
	ds_read_b128 v[202:205], v161 offset:52224
	ds_read_b128 v[206:209], v161 offset:53248
	ds_read_b128 v[210:213], v161 offset:54272
	ds_read_b128 v[214:217], v161 offset:55296
	ds_read_b128 v[218:221], v161 offset:56320
	global_load_lds_dwordx4 v138, s[36:37]
	s_add_i32 m0, s81, 0x2000
	s_add_u32 s34, s34, 0x104000
	s_addc_u32 s35, s35, 0
	global_load_lds_dwordx4 v134, s[36:37]
	s_add_i32 s36, s83, s38
	s_mov_b32 m0, s36
	s_nop 0
	global_load_lds_dwordx4 v138, s[34:35]
	s_add_i32 m0, s36, 0x2000
	s_nop 0
	global_load_lds_dwordx4 v134, s[34:35]
	s_mov_b32 m0, s58
	s_nop 0
	global_load_lds_dwordx4 v140, s[30:31]
	s_mov_b32 m0, s59
	s_nop 0
	global_load_lds_dwordx4 v136, s[30:31]
	s_waitcnt vmcnt(8)
	s_waitcnt lgkmcnt(0)
	s_barrier
	s_waitcnt lgkmcnt(0)
	v_mfma_f32_16x16x32_bf16 v[30:33], v[130:133], v[190:193], v[30:33]
	v_mfma_f32_16x16x32_bf16 v[30:33], v[162:165], v[194:197], v[30:33]
	v_mfma_f32_16x16x32_bf16 v[26:29], v[166:169], v[190:193], v[26:29]
	v_mfma_f32_16x16x32_bf16 v[26:29], v[170:173], v[194:197], v[26:29]
	v_mfma_f32_16x16x32_bf16 v[22:25], v[130:133], v[198:201], v[22:25]
	v_mfma_f32_16x16x32_bf16 v[22:25], v[162:165], v[202:205], v[22:25]
	v_mfma_f32_16x16x32_bf16 v[18:21], v[166:169], v[198:201], v[18:21]
	v_mfma_f32_16x16x32_bf16 v[18:21], v[170:173], v[202:205], v[18:21]
	v_mfma_f32_16x16x32_bf16 v[14:17], v[130:133], v[206:209], v[14:17]
	v_mfma_f32_16x16x32_bf16 v[14:17], v[162:165], v[210:213], v[14:17]
	v_mfma_f32_16x16x32_bf16 v[10:13], v[166:169], v[206:209], v[10:13]
	v_mfma_f32_16x16x32_bf16 v[10:13], v[170:173], v[210:213], v[10:13]
	v_mfma_f32_16x16x32_bf16 v[6:9], v[130:133], v[214:217], v[6:9]
	v_mfma_f32_16x16x32_bf16 v[6:9], v[162:165], v[218:221], v[6:9]
	v_mfma_f32_16x16x32_bf16 v[2:5], v[166:169], v[214:217], v[2:5]
	v_mfma_f32_16x16x32_bf16 v[2:5], v[170:173], v[218:221], v[2:5]
	v_mfma_f32_16x16x32_bf16 v[94:97], v[174:177], v[190:193], v[94:97]
	v_mfma_f32_16x16x32_bf16 v[94:97], v[178:181], v[194:197], v[94:97]
	v_mfma_f32_16x16x32_bf16 v[90:93], v[182:185], v[190:193], v[90:93]
	v_mfma_f32_16x16x32_bf16 v[90:93], v[186:189], v[194:197], v[90:93]
	v_mfma_f32_16x16x32_bf16 v[86:89], v[174:177], v[198:201], v[86:89]
	v_mfma_f32_16x16x32_bf16 v[86:89], v[178:181], v[202:205], v[86:89]
	v_mfma_f32_16x16x32_bf16 v[82:85], v[182:185], v[198:201], v[82:85]
	v_mfma_f32_16x16x32_bf16 v[82:85], v[186:189], v[202:205], v[82:85]
	v_mfma_f32_16x16x32_bf16 v[78:81], v[174:177], v[206:209], v[78:81]
	v_mfma_f32_16x16x32_bf16 v[78:81], v[178:181], v[210:213], v[78:81]
	v_mfma_f32_16x16x32_bf16 v[74:77], v[182:185], v[206:209], v[74:77]
	v_mfma_f32_16x16x32_bf16 v[74:77], v[186:189], v[210:213], v[74:77]
	v_mfma_f32_16x16x32_bf16 v[70:73], v[174:177], v[214:217], v[70:73]
	v_mfma_f32_16x16x32_bf16 v[70:73], v[178:181], v[218:221], v[70:73]
	v_mfma_f32_16x16x32_bf16 v[66:69], v[182:185], v[214:217], v[66:69]
	v_mfma_f32_16x16x32_bf16 v[66:69], v[186:189], v[218:221], v[66:69]
	s_barrier
	s_add_i32 s80, s80, 2
	s_add_u32 s26, s26, 0x8000
	s_addc_u32 s27, s27, 0
	s_add_u32 s78, s78, 0x8000
	s_addc_u32 s79, s79, 0
	s_cmp_gt_u32 s80, 61

.LBB0_1087:
	s_ashr_i32 s25, s24, 31
	s_lshl_b64 s[26:27], s[24:25], 21
	s_add_u32 s26, s28, s26
	s_addc_u32 s27, s29, s27
	s_and_b64 s[30:31], s[6:7], exec
	s_cselect_b32 s25, s27, s37
	s_cselect_b32 s35, s26, s36
	s_ashr_i32 s23, s22, 31
	s_lshl_b64 s[30:31], s[22:23], 21
	s_add_u32 s30, s52, s30
	s_addc_u32 s31, s53, s31
	s_and_b64 s[40:41], s[6:7], exec
	s_cselect_b32 s23, s31, s39
	s_cselect_b32 s69, s30, s38
	s_add_u32 s36, s36, 0x104000
	s_addc_u32 s37, s37, 0
	s_add_u32 s70, s38, 0x8000
	s_addc_u32 s71, s39, 0
	s_mov_b32 s72, -2
	s_waitcnt lgkmcnt(0)
	ds_read_b128 v[130:133], v209
	ds_read_b128 v[134:137], v209 offset:1024
	ds_read_b128 v[138:141], v209 offset:2048
	ds_read_b128 v[142:145], v209 offset:3072
	ds_read_b128 v[146:149], v210
	ds_read_b128 v[150:153], v210 offset:1024
	ds_read_b128 v[154:157], v210 offset:2048
	ds_read_b128 v[158:161], v210 offset:3072
	s_add_u32 s38, s36, 0xfff04000
	s_addc_u32 s39, s37, -1
	s_cmp_eq_u32 s72, 60
	s_cselect_b32 s42, s35, s38
	s_cselect_b32 s43, s25, s39
	s_cselect_b32 s40, s69, s70
	s_cselect_b32 s41, s23, s71
	s_add_u32 s38, s42, 0x4000
	s_addc_u32 s39, s43, 0
	s_add_i32 m0, s47, 0xc000
	ds_read_b128 v[162:165], v211
	ds_read_b128 v[166:169], v211 offset:1024
	ds_read_b128 v[170:173], v211 offset:2048
	ds_read_b128 v[174:177], v211 offset:3072
	ds_read_b128 v[196:199], v211 offset:4096
	ds_read_b128 v[200:203], v211 offset:5120
	ds_read_b128 v[214:217], v211 offset:6144
	ds_read_b128 v[218:221], v211 offset:7168
	global_load_lds_dwordx4 v188, s[36:37]
	s_add_i32 m0, s47, 0xe000
	s_nop 0
	global_load_lds_dwordx4 v190, s[36:37]
	s_waitcnt vmcnt(24)
	s_waitcnt lgkmcnt(0)
	s_barrier
	s_waitcnt lgkmcnt(0)
	v_mfma_f32_16x16x32_bf16 v[126:129], v[130:133], v[162:165], 0
	v_mfma_f32_16x16x32_bf16 v[126:129], v[134:137], v[166:169], v[126:129]
	v_mfma_f32_16x16x32_bf16 v[122:125], v[138:141], v[162:165], 0
	v_mfma_f32_16x16x32_bf16 v[122:125], v[142:145], v[166:169], v[122:125]
	v_mfma_f32_16x16x32_bf16 v[110:113], v[130:133], v[170:173], 0
	v_mfma_f32_16x16x32_bf16 v[110:113], v[134:137], v[174:177], v[110:113]
	v_mfma_f32_16x16x32_bf16 v[106:109], v[138:141], v[170:173], 0
	v_mfma_f32_16x16x32_bf16 v[106:109], v[142:145], v[174:177], v[106:109]
	v_mfma_f32_16x16x32_bf16 v[94:97], v[130:133], v[196:199], 0
	v_mfma_f32_16x16x32_bf16 v[94:97], v[134:137], v[200:203], v[94:97]
	v_mfma_f32_16x16x32_bf16 v[90:93], v[138:141], v[196:199], 0
	v_mfma_f32_16x16x32_bf16 v[90:93], v[142:145], v[200:203], v[90:93]
	v_mfma_f32_16x16x32_bf16 v[78:81], v[130:133], v[214:217], 0
	v_mfma_f32_16x16x32_bf16 v[78:81], v[134:137], v[218:221], v[78:81]
	v_mfma_f32_16x16x32_bf16 v[74:77], v[138:141], v[214:217], 0
	v_mfma_f32_16x16x32_bf16 v[74:77], v[142:145], v[218:221], v[74:77]
	v_mfma_f32_16x16x32_bf16 v[118:121], v[146:149], v[162:165], 0
	v_mfma_f32_16x16x32_bf16 v[118:121], v[150:153], v[166:169], v[118:121]
	v_mfma_f32_16x16x32_bf16 v[114:117], v[154:157], v[162:165], 0
	v_mfma_f32_16x16x32_bf16 v[114:117], v[158:161], v[166:169], v[114:117]
	v_mfma_f32_16x16x32_bf16 v[102:105], v[146:149], v[170:173], 0
	v_mfma_f32_16x16x32_bf16 v[102:105], v[150:153], v[174:177], v[102:105]
	v_mfma_f32_16x16x32_bf16 v[98:101], v[154:157], v[170:173], 0
	v_mfma_f32_16x16x32_bf16 v[98:101], v[158:161], v[174:177], v[98:101]
	v_mfma_f32_16x16x32_bf16 v[86:89], v[146:149], v[196:199], 0
	v_mfma_f32_16x16x32_bf16 v[86:89], v[150:153], v[200:203], v[86:89]
	v_mfma_f32_16x16x32_bf16 v[82:85], v[154:157], v[196:199], 0
	v_mfma_f32_16x16x32_bf16 v[82:85], v[158:161], v[200:203], v[82:85]
	v_mfma_f32_16x16x32_bf16 v[70:73], v[146:149], v[214:217], 0
	v_mfma_f32_16x16x32_bf16 v[70:73], v[150:153], v[218:221], v[70:73]
	v_mfma_f32_16x16x32_bf16 v[66:69], v[154:157], v[214:217], 0
	v_mfma_f32_16x16x32_bf16 v[66:69], v[158:161], v[218:221], v[66:69]
	s_barrier
	s_add_i32 s73, s66, s46
	s_mov_b32 m0, s73
	ds_read_b128 v[162:165], v211 offset:16384
	ds_read_b128 v[166:169], v211 offset:17408
	ds_read_b128 v[170:173], v211 offset:18432
	ds_read_b128 v[174:177], v211 offset:19456
	ds_read_b128 v[196:199], v211 offset:20480
	ds_read_b128 v[200:203], v211 offset:21504
	ds_read_b128 v[214:217], v211 offset:22528
	ds_read_b128 v[218:221], v211 offset:23552
	global_load_lds_dwordx4 v180, s[40:41]
	s_add_i32 m0, s73, 0x2000
	s_add_u32 s74, s40, 0x100000
	s_addc_u32 s75, s41, 0
	s_add_i32 s73, s67, s46
	global_load_lds_dwordx4 v184, s[40:41]
	s_mov_b32 m0, s73
	s_nop 0
	global_load_lds_dwordx4 v180, s[74:75]
	s_add_i32 m0, s73, 0x2000
	s_nop 0
	global_load_lds_dwordx4 v184, s[74:75]
	s_mov_b32 m0, s47
	s_nop 0
	global_load_lds_dwordx4 v178, s[42:43]
	s_mov_b32 m0, s59
	s_nop 0
	global_load_lds_dwordx4 v182, s[42:43]
	s_waitcnt vmcnt(8)
	s_waitcnt lgkmcnt(0)
	s_barrier
	s_waitcnt lgkmcnt(0)
	v_mfma_f32_16x16x32_bf16 v[62:65], v[130:133], v[162:165], 0
	v_mfma_f32_16x16x32_bf16 v[62:65], v[134:137], v[166:169], v[62:65]
	v_mfma_f32_16x16x32_bf16 v[58:61], v[138:141], v[162:165], 0
	v_mfma_f32_16x16x32_bf16 v[58:61], v[142:145], v[166:169], v[58:61]
	v_mfma_f32_16x16x32_bf16 v[46:49], v[130:133], v[170:173], 0
	v_mfma_f32_16x16x32_bf16 v[46:49], v[134:137], v[174:177], v[46:49]
	v_mfma_f32_16x16x32_bf16 v[42:45], v[138:141], v[170:173], 0
	v_mfma_f32_16x16x32_bf16 v[42:45], v[142:145], v[174:177], v[42:45]
	v_mfma_f32_16x16x32_bf16 v[30:33], v[130:133], v[196:199], 0
	v_mfma_f32_16x16x32_bf16 v[30:33], v[134:137], v[200:203], v[30:33]
	v_mfma_f32_16x16x32_bf16 v[26:29], v[138:141], v[196:199], 0
	v_mfma_f32_16x16x32_bf16 v[26:29], v[142:145], v[200:203], v[26:29]
	v_mfma_f32_16x16x32_bf16 v[14:17], v[130:133], v[214:217], 0
	v_mfma_f32_16x16x32_bf16 v[14:17], v[134:137], v[218:221], v[14:17]
	v_mfma_f32_16x16x32_bf16 v[10:13], v[138:141], v[214:217], 0
	v_mfma_f32_16x16x32_bf16 v[10:13], v[142:145], v[218:221], v[10:13]
	v_mfma_f32_16x16x32_bf16 v[54:57], v[146:149], v[162:165], 0
	v_mfma_f32_16x16x32_bf16 v[54:57], v[150:153], v[166:169], v[54:57]
	v_mfma_f32_16x16x32_bf16 v[50:53], v[154:157], v[162:165], 0
	v_mfma_f32_16x16x32_bf16 v[50:53], v[158:161], v[166:169], v[50:53]
	v_mfma_f32_16x16x32_bf16 v[38:41], v[146:149], v[170:173], 0
	v_mfma_f32_16x16x32_bf16 v[38:41], v[150:153], v[174:177], v[38:41]
	v_mfma_f32_16x16x32_bf16 v[34:37], v[154:157], v[170:173], 0
	v_mfma_f32_16x16x32_bf16 v[34:37], v[158:161], v[174:177], v[34:37]
	v_mfma_f32_16x16x32_bf16 v[22:25], v[146:149], v[196:199], 0
	v_mfma_f32_16x16x32_bf16 v[22:25], v[150:153], v[200:203], v[22:25]
	v_mfma_f32_16x16x32_bf16 v[18:21], v[154:157], v[196:199], 0
	v_mfma_f32_16x16x32_bf16 v[18:21], v[158:161], v[200:203], v[18:21]
	v_mfma_f32_16x16x32_bf16 v[6:9], v[146:149], v[214:217], 0
	v_mfma_f32_16x16x32_bf16 v[6:9], v[150:153], v[218:221], v[6:9]
	v_mfma_f32_16x16x32_bf16 v[2:5], v[154:157], v[214:217], 0
	v_mfma_f32_16x16x32_bf16 v[2:5], v[158:161], v[218:221], v[2:5]
	s_barrier
	s_add_i32 s73, 0, 0x18000
	s_add_i32 s74, 0, 0x1c000
	v_add_u32_e32 v142, s73, v208
	v_add_u32_e32 v158, s74, v208
	ds_read_b128 v[130:133], v142
	ds_read_b128 v[134:137], v142 offset:1024
	ds_read_b128 v[138:141], v142 offset:2048
	ds_read_b128 v[142:145], v142 offset:3072
	ds_read_b128 v[146:149], v158
	ds_read_b128 v[150:153], v158 offset:1024
	ds_read_b128 v[154:157], v158 offset:2048
	ds_read_b128 v[158:161], v158 offset:3072
	s_add_u32 s42, s42, 0x100000
	s_addc_u32 s43, s43, 0
	s_mov_b32 m0, s60
	ds_read_b128 v[162:165], v211 offset:32768
	ds_read_b128 v[166:169], v211 offset:33792
	ds_read_b128 v[170:173], v211 offset:34816
	ds_read_b128 v[174:177], v211 offset:35840
	ds_read_b128 v[196:199], v211 offset:36864
	ds_read_b128 v[200:203], v211 offset:37888
	ds_read_b128 v[214:217], v211 offset:38912
	ds_read_b128 v[218:221], v211 offset:39936
	global_load_lds_dwordx4 v178, s[42:43]
	s_mov_b32 m0, s61
	s_nop 0
	global_load_lds_dwordx4 v182, s[42:43]
	s_waitcnt vmcnt(8)
	s_waitcnt lgkmcnt(0)
	s_barrier
	s_waitcnt lgkmcnt(0)
	v_mfma_f32_16x16x32_bf16 v[126:129], v[130:133], v[162:165], v[126:129]
	v_mfma_f32_16x16x32_bf16 v[126:129], v[134:137], v[166:169], v[126:129]
	v_mfma_f32_16x16x32_bf16 v[122:125], v[138:141], v[162:165], v[122:125]
	v_mfma_f32_16x16x32_bf16 v[122:125], v[142:145], v[166:169], v[122:125]
	v_mfma_f32_16x16x32_bf16 v[110:113], v[130:133], v[170:173], v[110:113]
	v_mfma_f32_16x16x32_bf16 v[110:113], v[134:137], v[174:177], v[110:113]
	v_mfma_f32_16x16x32_bf16 v[106:109], v[138:141], v[170:173], v[106:109]
	v_mfma_f32_16x16x32_bf16 v[106:109], v[142:145], v[174:177], v[106:109]
	v_mfma_f32_16x16x32_bf16 v[94:97], v[130:133], v[196:199], v[94:97]
	v_mfma_f32_16x16x32_bf16 v[94:97], v[134:137], v[200:203], v[94:97]
	v_mfma_f32_16x16x32_bf16 v[90:93], v[138:141], v[196:199], v[90:93]
	v_mfma_f32_16x16x32_bf16 v[90:93], v[142:145], v[200:203], v[90:93]
	v_mfma_f32_16x16x32_bf16 v[78:81], v[130:133], v[214:217], v[78:81]
	v_mfma_f32_16x16x32_bf16 v[78:81], v[134:137], v[218:221], v[78:81]
	v_mfma_f32_16x16x32_bf16 v[74:77], v[138:141], v[214:217], v[74:77]
	v_mfma_f32_16x16x32_bf16 v[74:77], v[142:145], v[218:221], v[74:77]
	v_mfma_f32_16x16x32_bf16 v[118:121], v[146:149], v[162:165], v[118:121]
	v_mfma_f32_16x16x32_bf16 v[118:121], v[150:153], v[166:169], v[118:121]
	v_mfma_f32_16x16x32_bf16 v[114:117], v[154:157], v[162:165], v[114:117]
	v_mfma_f32_16x16x32_bf16 v[114:117], v[158:161], v[166:169], v[114:117]
	v_mfma_f32_16x16x32_bf16 v[102:105], v[146:149], v[170:173], v[102:105]
	v_mfma_f32_16x16x32_bf16 v[102:105], v[150:153], v[174:177], v[102:105]
	v_mfma_f32_16x16x32_bf16 v[98:101], v[154:157], v[170:173], v[98:101]
	v_mfma_f32_16x16x32_bf16 v[98:101], v[158:161], v[174:177], v[98:101]
	v_mfma_f32_16x16x32_bf16 v[86:89], v[146:149], v[196:199], v[86:89]
	v_mfma_f32_16x16x32_bf16 v[86:89], v[150:153], v[200:203], v[86:89]
	v_mfma_f32_16x16x32_bf16 v[82:85], v[154:157], v[196:199], v[82:85]
	v_mfma_f32_16x16x32_bf16 v[82:85], v[158:161], v[200:203], v[82:85]
	v_mfma_f32_16x16x32_bf16 v[70:73], v[146:149], v[214:217], v[70:73]
	v_mfma_f32_16x16x32_bf16 v[70:73], v[150:153], v[218:221], v[70:73]
	v_mfma_f32_16x16x32_bf16 v[66:69], v[154:157], v[214:217], v[66:69]
	v_mfma_f32_16x16x32_bf16 v[66:69], v[158:161], v[218:221], v[66:69]
	s_barrier
	s_add_u32 s42, s40, 0x4000
	s_addc_u32 s43, s41, 0
	s_add_i32 s73, s73, s46
	s_mov_b32 m0, s73
	ds_read_b128 v[162:165], v211 offset:49152
	ds_read_b128 v[166:169], v211 offset:50176
	ds_read_b128 v[170:173], v211 offset:51200
	ds_read_b128 v[174:177], v211 offset:52224
	ds_read_b128 v[196:199], v211 offset:53248
	ds_read_b128 v[200:203], v211 offset:54272
	ds_read_b128 v[214:217], v211 offset:55296
	ds_read_b128 v[218:221], v211 offset:56320
	global_load_lds_dwordx4 v180, s[42:43]
	s_add_i32 m0, s73, 0x2000
	s_add_u32 s40, s40, 0x104000
	s_addc_u32 s41, s41, 0
	global_load_lds_dwordx4 v184, s[42:43]
	s_add_i32 s42, s74, s46
	s_mov_b32 m0, s42
	s_nop 0
	global_load_lds_dwordx4 v180, s[40:41]
	s_add_i32 m0, s42, 0x2000
	s_nop 0
	global_load_lds_dwordx4 v184, s[40:41]
	s_mov_b32 m0, s64
	s_nop 0
	global_load_lds_dwordx4 v178, s[38:39]
	s_mov_b32 m0, s65
	s_nop 0
	global_load_lds_dwordx4 v182, s[38:39]
	s_waitcnt vmcnt(8)
	s_waitcnt lgkmcnt(0)
	s_barrier
	s_waitcnt lgkmcnt(0)
	v_mfma_f32_16x16x32_bf16 v[62:65], v[130:133], v[162:165], v[62:65]
	v_mfma_f32_16x16x32_bf16 v[62:65], v[134:137], v[166:169], v[62:65]
	v_mfma_f32_16x16x32_bf16 v[58:61], v[138:141], v[162:165], v[58:61]
	v_mfma_f32_16x16x32_bf16 v[58:61], v[142:145], v[166:169], v[58:61]
	v_mfma_f32_16x16x32_bf16 v[46:49], v[130:133], v[170:173], v[46:49]
	v_mfma_f32_16x16x32_bf16 v[46:49], v[134:137], v[174:177], v[46:49]
	v_mfma_f32_16x16x32_bf16 v[42:45], v[138:141], v[170:173], v[42:45]
	v_mfma_f32_16x16x32_bf16 v[42:45], v[142:145], v[174:177], v[42:45]
	v_mfma_f32_16x16x32_bf16 v[30:33], v[130:133], v[196:199], v[30:33]
	v_mfma_f32_16x16x32_bf16 v[30:33], v[134:137], v[200:203], v[30:33]
	v_mfma_f32_16x16x32_bf16 v[26:29], v[138:141], v[196:199], v[26:29]
	v_mfma_f32_16x16x32_bf16 v[26:29], v[142:145], v[200:203], v[26:29]
	v_mfma_f32_16x16x32_bf16 v[14:17], v[130:133], v[214:217], v[14:17]
	v_mfma_f32_16x16x32_bf16 v[14:17], v[134:137], v[218:221], v[14:17]
	v_mfma_f32_16x16x32_bf16 v[10:13], v[138:141], v[214:217], v[10:13]
	v_mfma_f32_16x16x32_bf16 v[10:13], v[142:145], v[218:221], v[10:13]
	v_mfma_f32_16x16x32_bf16 v[54:57], v[146:149], v[162:165], v[54:57]
	v_mfma_f32_16x16x32_bf16 v[54:57], v[150:153], v[166:169], v[54:57]
	v_mfma_f32_16x16x32_bf16 v[50:53], v[154:157], v[162:165], v[50:53]
	v_mfma_f32_16x16x32_bf16 v[50:53], v[158:161], v[166:169], v[50:53]
	v_mfma_f32_16x16x32_bf16 v[38:41], v[146:149], v[170:173], v[38:41]
	v_mfma_f32_16x16x32_bf16 v[38:41], v[150:153], v[174:177], v[38:41]
	v_mfma_f32_16x16x32_bf16 v[34:37], v[154:157], v[170:173], v[34:37]
	v_mfma_f32_16x16x32_bf16 v[34:37], v[158:161], v[174:177], v[34:37]
	v_mfma_f32_16x16x32_bf16 v[22:25], v[146:149], v[196:199], v[22:25]
	v_mfma_f32_16x16x32_bf16 v[22:25], v[150:153], v[200:203], v[22:25]
	v_mfma_f32_16x16x32_bf16 v[18:21], v[154:157], v[196:199], v[18:21]
	v_mfma_f32_16x16x32_bf16 v[18:21], v[158:161], v[200:203], v[18:21]
	v_mfma_f32_16x16x32_bf16 v[6:9], v[146:149], v[214:217], v[6:9]
	v_mfma_f32_16x16x32_bf16 v[6:9], v[150:153], v[218:221], v[6:9]
	v_mfma_f32_16x16x32_bf16 v[2:5], v[154:157], v[214:217], v[2:5]
	v_mfma_f32_16x16x32_bf16 v[2:5], v[158:161], v[218:221], v[2:5]
	s_barrier
	s_add_i32 s72, s72, 2
	s_add_u32 s36, s36, 0x8000
	s_addc_u32 s37, s37, 0
	s_add_u32 s70, s70, 0x8000
	s_addc_u32 s71, s71, 0
	s_cmp_gt_u32 s72, 61

.LBB0_1214:
	s_ashr_i32 s21, s20, 31
	s_lshl_b64 s[22:23], s[20:21], 21
	s_add_u32 s22, s10, s22
	s_addc_u32 s23, s11, s23
	s_and_b64 s[24:25], s[4:5], exec
	s_cselect_b32 s21, s23, s29
	s_cselect_b32 s56, s22, s28
	s_ashr_i32 s19, s18, 31
	s_lshl_b64 s[24:25], s[18:19], 21
	s_add_u32 s24, s65, s24
	v_readlane_b32 s19, v251, 50
	s_addc_u32 s25, s19, s25
	s_and_b64 s[34:35], s[4:5], exec
	s_cselect_b32 s19, s25, s31
	s_cselect_b32 s57, s24, s30
	s_add_u32 s28, s28, 0x104000
	s_addc_u32 s29, s29, 0
	s_add_u32 s59, s30, 0x8000
	s_addc_u32 s60, s31, 0
	s_mov_b32 s61, -2
	ds_read_b128 v[160:163], v154
	ds_read_b128 v[164:167], v154 offset:1024
	ds_read_b128 v[168:171], v154 offset:2048
	ds_read_b128 v[172:175], v154 offset:3072
	ds_read_b128 v[176:179], v155
	ds_read_b128 v[180:183], v155 offset:1024
	ds_read_b128 v[184:187], v155 offset:2048
	ds_read_b128 v[188:191], v155 offset:3072
	s_add_u32 s30, s28, 0xfff04000
	s_addc_u32 s31, s29, -1
	s_cmp_eq_u32 s61, 60
	s_cselect_b32 s36, s56, s30
	s_cselect_b32 s37, s21, s31
	s_cselect_b32 s34, s57, s59
	s_cselect_b32 s35, s19, s60
	s_add_u32 s30, s36, 0x4000
	s_addc_u32 s31, s37, 0
	s_add_i32 m0, s39, 0xc000
	ds_read_b128 v[192:195], v156
	ds_read_b128 v[196:199], v156 offset:1024
	ds_read_b128 v[200:203], v156 offset:2048
	ds_read_b128 v[204:207], v156 offset:3072
	ds_read_b128 v[208:211], v156 offset:4096
	ds_read_b128 v[212:215], v156 offset:5120
	ds_read_b128 v[216:219], v156 offset:6144
	ds_read_b128 v[220:223], v156 offset:7168
	global_load_lds_dwordx4 v140, s[28:29]
	s_add_i32 m0, s39, 0xe000
	s_nop 0
	global_load_lds_dwordx4 v142, s[28:29]
	s_waitcnt vmcnt(24)
	s_waitcnt lgkmcnt(0)
	s_barrier
	s_waitcnt lgkmcnt(0)
	v_mfma_f32_16x16x32_bf16 v[126:129], v[160:163], v[192:195], 0
	v_mfma_f32_16x16x32_bf16 v[126:129], v[164:167], v[196:199], v[126:129]
	v_mfma_f32_16x16x32_bf16 v[122:125], v[168:171], v[192:195], 0
	v_mfma_f32_16x16x32_bf16 v[122:125], v[172:175], v[196:199], v[122:125]
	v_mfma_f32_16x16x32_bf16 v[110:113], v[160:163], v[200:203], 0
	v_mfma_f32_16x16x32_bf16 v[110:113], v[164:167], v[204:207], v[110:113]
	v_mfma_f32_16x16x32_bf16 v[106:109], v[168:171], v[200:203], 0
	v_mfma_f32_16x16x32_bf16 v[106:109], v[172:175], v[204:207], v[106:109]
	v_mfma_f32_16x16x32_bf16 v[94:97], v[160:163], v[208:211], 0
	v_mfma_f32_16x16x32_bf16 v[94:97], v[164:167], v[212:215], v[94:97]
	v_mfma_f32_16x16x32_bf16 v[90:93], v[168:171], v[208:211], 0
	v_mfma_f32_16x16x32_bf16 v[90:93], v[172:175], v[212:215], v[90:93]
	v_mfma_f32_16x16x32_bf16 v[78:81], v[160:163], v[216:219], 0
	v_mfma_f32_16x16x32_bf16 v[78:81], v[164:167], v[220:223], v[78:81]
	v_mfma_f32_16x16x32_bf16 v[74:77], v[168:171], v[216:219], 0
	v_mfma_f32_16x16x32_bf16 v[74:77], v[172:175], v[220:223], v[74:77]
	v_mfma_f32_16x16x32_bf16 v[118:121], v[176:179], v[192:195], 0
	v_mfma_f32_16x16x32_bf16 v[118:121], v[180:183], v[196:199], v[118:121]
	v_mfma_f32_16x16x32_bf16 v[114:117], v[184:187], v[192:195], 0
	v_mfma_f32_16x16x32_bf16 v[114:117], v[188:191], v[196:199], v[114:117]
	v_mfma_f32_16x16x32_bf16 v[102:105], v[176:179], v[200:203], 0
	v_mfma_f32_16x16x32_bf16 v[102:105], v[180:183], v[204:207], v[102:105]
	v_mfma_f32_16x16x32_bf16 v[98:101], v[184:187], v[200:203], 0
	v_mfma_f32_16x16x32_bf16 v[98:101], v[188:191], v[204:207], v[98:101]
	v_mfma_f32_16x16x32_bf16 v[86:89], v[176:179], v[208:211], 0
	v_mfma_f32_16x16x32_bf16 v[86:89], v[180:183], v[212:215], v[86:89]
	v_mfma_f32_16x16x32_bf16 v[82:85], v[184:187], v[208:211], 0
	v_mfma_f32_16x16x32_bf16 v[82:85], v[188:191], v[212:215], v[82:85]
	v_mfma_f32_16x16x32_bf16 v[70:73], v[176:179], v[216:219], 0
	v_mfma_f32_16x16x32_bf16 v[70:73], v[180:183], v[220:223], v[70:73]
	v_mfma_f32_16x16x32_bf16 v[66:69], v[184:187], v[216:219], 0
	v_mfma_f32_16x16x32_bf16 v[66:69], v[188:191], v[220:223], v[66:69]
	s_barrier
	s_add_i32 s62, s47, s38
	s_mov_b32 m0, s62
	ds_read_b128 v[192:195], v156 offset:16384
	ds_read_b128 v[196:199], v156 offset:17408
	ds_read_b128 v[200:203], v156 offset:18432
	ds_read_b128 v[204:207], v156 offset:19456
	ds_read_b128 v[208:211], v156 offset:20480
	ds_read_b128 v[212:215], v156 offset:21504
	ds_read_b128 v[216:219], v156 offset:22528
	ds_read_b128 v[220:223], v156 offset:23552
	global_load_lds_dwordx4 v134, s[34:35]
	s_add_i32 m0, s62, 0x2000
	s_add_u32 s62, s34, 0x100000
	s_addc_u32 s63, s35, 0
	s_add_i32 s64, s54, s38
	global_load_lds_dwordx4 v130, s[34:35]
	s_mov_b32 m0, s64
	s_nop 0
	global_load_lds_dwordx4 v134, s[62:63]
	s_add_i32 m0, s64, 0x2000
	s_nop 0
	global_load_lds_dwordx4 v130, s[62:63]
	s_mov_b32 m0, s39
	s_nop 0
	global_load_lds_dwordx4 v136, s[36:37]
	s_mov_b32 m0, s40
	s_nop 0
	global_load_lds_dwordx4 v132, s[36:37]
	s_waitcnt vmcnt(8)
	s_waitcnt lgkmcnt(0)
	s_barrier
	s_waitcnt lgkmcnt(0)
	v_mfma_f32_16x16x32_bf16 v[62:65], v[160:163], v[192:195], 0
	v_mfma_f32_16x16x32_bf16 v[62:65], v[164:167], v[196:199], v[62:65]
	v_mfma_f32_16x16x32_bf16 v[58:61], v[168:171], v[192:195], 0
	v_mfma_f32_16x16x32_bf16 v[58:61], v[172:175], v[196:199], v[58:61]
	v_mfma_f32_16x16x32_bf16 v[46:49], v[160:163], v[200:203], 0
	v_mfma_f32_16x16x32_bf16 v[46:49], v[164:167], v[204:207], v[46:49]
	v_mfma_f32_16x16x32_bf16 v[42:45], v[168:171], v[200:203], 0
	v_mfma_f32_16x16x32_bf16 v[42:45], v[172:175], v[204:207], v[42:45]
	v_mfma_f32_16x16x32_bf16 v[30:33], v[160:163], v[208:211], 0
	v_mfma_f32_16x16x32_bf16 v[30:33], v[164:167], v[212:215], v[30:33]
	v_mfma_f32_16x16x32_bf16 v[26:29], v[168:171], v[208:211], 0
	v_mfma_f32_16x16x32_bf16 v[26:29], v[172:175], v[212:215], v[26:29]
	v_mfma_f32_16x16x32_bf16 v[14:17], v[160:163], v[216:219], 0
	v_mfma_f32_16x16x32_bf16 v[14:17], v[164:167], v[220:223], v[14:17]
	v_mfma_f32_16x16x32_bf16 v[10:13], v[168:171], v[216:219], 0
	v_mfma_f32_16x16x32_bf16 v[10:13], v[172:175], v[220:223], v[10:13]
	v_mfma_f32_16x16x32_bf16 v[54:57], v[176:179], v[192:195], 0
	v_mfma_f32_16x16x32_bf16 v[54:57], v[180:183], v[196:199], v[54:57]
	v_mfma_f32_16x16x32_bf16 v[50:53], v[184:187], v[192:195], 0
	v_mfma_f32_16x16x32_bf16 v[50:53], v[188:191], v[196:199], v[50:53]
	v_mfma_f32_16x16x32_bf16 v[38:41], v[176:179], v[200:203], 0
	v_mfma_f32_16x16x32_bf16 v[38:41], v[180:183], v[204:207], v[38:41]
	v_mfma_f32_16x16x32_bf16 v[34:37], v[184:187], v[200:203], 0
	v_mfma_f32_16x16x32_bf16 v[34:37], v[188:191], v[204:207], v[34:37]
	v_mfma_f32_16x16x32_bf16 v[22:25], v[176:179], v[208:211], 0
	v_mfma_f32_16x16x32_bf16 v[22:25], v[180:183], v[212:215], v[22:25]
	v_mfma_f32_16x16x32_bf16 v[18:21], v[184:187], v[208:211], 0
	v_mfma_f32_16x16x32_bf16 v[18:21], v[188:191], v[212:215], v[18:21]
	v_mfma_f32_16x16x32_bf16 v[6:9], v[176:179], v[216:219], 0
	v_mfma_f32_16x16x32_bf16 v[6:9], v[180:183], v[220:223], v[6:9]
	v_mfma_f32_16x16x32_bf16 v[2:5], v[184:187], v[216:219], 0
	v_mfma_f32_16x16x32_bf16 v[2:5], v[188:191], v[220:223], v[2:5]
	s_barrier
	s_add_i32 s62, 0, 0x18000
	v_add_u32_e32 v138, s62, v153
	s_add_i32 s63, 0, 0x1c000
	ds_read_b128 v[160:163], v138
	ds_read_b128 v[164:167], v138 offset:1024
	ds_read_b128 v[168:171], v138 offset:2048
	ds_read_b128 v[172:175], v138 offset:3072
	v_add_u32_e32 v138, s63, v153
	ds_read_b128 v[176:179], v138
	ds_read_b128 v[180:183], v138 offset:1024
	ds_read_b128 v[184:187], v138 offset:2048
	ds_read_b128 v[188:191], v138 offset:3072
	s_add_u32 s36, s36, 0x100000
	s_addc_u32 s37, s37, 0
	s_mov_b32 m0, s41
	ds_read_b128 v[192:195], v156 offset:32768
	ds_read_b128 v[196:199], v156 offset:33792
	ds_read_b128 v[200:203], v156 offset:34816
	ds_read_b128 v[204:207], v156 offset:35840
	ds_read_b128 v[208:211], v156 offset:36864
	ds_read_b128 v[212:215], v156 offset:37888
	ds_read_b128 v[216:219], v156 offset:38912
	ds_read_b128 v[220:223], v156 offset:39936
	global_load_lds_dwordx4 v136, s[36:37]
	s_mov_b32 m0, s42
	s_nop 0
	global_load_lds_dwordx4 v132, s[36:37]
	s_waitcnt vmcnt(8)
	s_waitcnt lgkmcnt(0)
	s_barrier
	s_waitcnt lgkmcnt(0)
	v_mfma_f32_16x16x32_bf16 v[126:129], v[160:163], v[192:195], v[126:129]
	v_mfma_f32_16x16x32_bf16 v[126:129], v[164:167], v[196:199], v[126:129]
	v_mfma_f32_16x16x32_bf16 v[122:125], v[168:171], v[192:195], v[122:125]
	v_mfma_f32_16x16x32_bf16 v[122:125], v[172:175], v[196:199], v[122:125]
	v_mfma_f32_16x16x32_bf16 v[110:113], v[160:163], v[200:203], v[110:113]
	v_mfma_f32_16x16x32_bf16 v[110:113], v[164:167], v[204:207], v[110:113]
	v_mfma_f32_16x16x32_bf16 v[106:109], v[168:171], v[200:203], v[106:109]
	v_mfma_f32_16x16x32_bf16 v[106:109], v[172:175], v[204:207], v[106:109]
	v_mfma_f32_16x16x32_bf16 v[94:97], v[160:163], v[208:211], v[94:97]
	v_mfma_f32_16x16x32_bf16 v[94:97], v[164:167], v[212:215], v[94:97]
	v_mfma_f32_16x16x32_bf16 v[90:93], v[168:171], v[208:211], v[90:93]
	v_mfma_f32_16x16x32_bf16 v[90:93], v[172:175], v[212:215], v[90:93]
	v_mfma_f32_16x16x32_bf16 v[78:81], v[160:163], v[216:219], v[78:81]
	v_mfma_f32_16x16x32_bf16 v[78:81], v[164:167], v[220:223], v[78:81]
	v_mfma_f32_16x16x32_bf16 v[74:77], v[168:171], v[216:219], v[74:77]
	v_mfma_f32_16x16x32_bf16 v[74:77], v[172:175], v[220:223], v[74:77]
	v_mfma_f32_16x16x32_bf16 v[118:121], v[176:179], v[192:195], v[118:121]
	v_mfma_f32_16x16x32_bf16 v[118:121], v[180:183], v[196:199], v[118:121]
	v_mfma_f32_16x16x32_bf16 v[114:117], v[184:187], v[192:195], v[114:117]
	v_mfma_f32_16x16x32_bf16 v[114:117], v[188:191], v[196:199], v[114:117]
	v_mfma_f32_16x16x32_bf16 v[102:105], v[176:179], v[200:203], v[102:105]
	v_mfma_f32_16x16x32_bf16 v[102:105], v[180:183], v[204:207], v[102:105]
	v_mfma_f32_16x16x32_bf16 v[98:101], v[184:187], v[200:203], v[98:101]
	v_mfma_f32_16x16x32_bf16 v[98:101], v[188:191], v[204:207], v[98:101]
	v_mfma_f32_16x16x32_bf16 v[86:89], v[176:179], v[208:211], v[86:89]
	v_mfma_f32_16x16x32_bf16 v[86:89], v[180:183], v[212:215], v[86:89]
	v_mfma_f32_16x16x32_bf16 v[82:85], v[184:187], v[208:211], v[82:85]
	v_mfma_f32_16x16x32_bf16 v[82:85], v[188:191], v[212:215], v[82:85]
	v_mfma_f32_16x16x32_bf16 v[70:73], v[176:179], v[216:219], v[70:73]
	v_mfma_f32_16x16x32_bf16 v[70:73], v[180:183], v[220:223], v[70:73]
	v_mfma_f32_16x16x32_bf16 v[66:69], v[184:187], v[216:219], v[66:69]
	v_mfma_f32_16x16x32_bf16 v[66:69], v[188:191], v[220:223], v[66:69]
	s_barrier
	s_add_u32 s36, s34, 0x4000
	s_addc_u32 s37, s35, 0
	s_add_i32 s62, s62, s38
	s_mov_b32 m0, s62
	ds_read_b128 v[192:195], v156 offset:49152
	ds_read_b128 v[196:199], v156 offset:50176
	ds_read_b128 v[200:203], v156 offset:51200
	ds_read_b128 v[204:207], v156 offset:52224
	ds_read_b128 v[208:211], v156 offset:53248
	ds_read_b128 v[212:215], v156 offset:54272
	ds_read_b128 v[216:219], v156 offset:55296
	ds_read_b128 v[220:223], v156 offset:56320
	global_load_lds_dwordx4 v134, s[36:37]
	s_add_i32 m0, s62, 0x2000
	s_add_u32 s34, s34, 0x104000
	s_addc_u32 s35, s35, 0
	global_load_lds_dwordx4 v130, s[36:37]
	s_add_i32 s36, s63, s38
	s_mov_b32 m0, s36
	s_nop 0
	global_load_lds_dwordx4 v134, s[34:35]
	s_add_i32 m0, s36, 0x2000
	s_nop 0
	global_load_lds_dwordx4 v130, s[34:35]
	s_mov_b32 m0, s45
	s_nop 0
	global_load_lds_dwordx4 v136, s[30:31]
	s_mov_b32 m0, s46
	s_nop 0
	global_load_lds_dwordx4 v132, s[30:31]
	s_waitcnt vmcnt(8)
	s_waitcnt lgkmcnt(0)
	s_barrier
	s_waitcnt lgkmcnt(0)
	v_mfma_f32_16x16x32_bf16 v[62:65], v[160:163], v[192:195], v[62:65]
	v_mfma_f32_16x16x32_bf16 v[62:65], v[164:167], v[196:199], v[62:65]
	v_mfma_f32_16x16x32_bf16 v[58:61], v[168:171], v[192:195], v[58:61]
	v_mfma_f32_16x16x32_bf16 v[58:61], v[172:175], v[196:199], v[58:61]
	v_mfma_f32_16x16x32_bf16 v[46:49], v[160:163], v[200:203], v[46:49]
	v_mfma_f32_16x16x32_bf16 v[46:49], v[164:167], v[204:207], v[46:49]
	v_mfma_f32_16x16x32_bf16 v[42:45], v[168:171], v[200:203], v[42:45]
	v_mfma_f32_16x16x32_bf16 v[42:45], v[172:175], v[204:207], v[42:45]
	v_mfma_f32_16x16x32_bf16 v[30:33], v[160:163], v[208:211], v[30:33]
	v_mfma_f32_16x16x32_bf16 v[30:33], v[164:167], v[212:215], v[30:33]
	v_mfma_f32_16x16x32_bf16 v[26:29], v[168:171], v[208:211], v[26:29]
	v_mfma_f32_16x16x32_bf16 v[26:29], v[172:175], v[212:215], v[26:29]
	v_mfma_f32_16x16x32_bf16 v[14:17], v[160:163], v[216:219], v[14:17]
	v_mfma_f32_16x16x32_bf16 v[14:17], v[164:167], v[220:223], v[14:17]
	v_mfma_f32_16x16x32_bf16 v[10:13], v[168:171], v[216:219], v[10:13]
	v_mfma_f32_16x16x32_bf16 v[10:13], v[172:175], v[220:223], v[10:13]
	v_mfma_f32_16x16x32_bf16 v[54:57], v[176:179], v[192:195], v[54:57]
	v_mfma_f32_16x16x32_bf16 v[54:57], v[180:183], v[196:199], v[54:57]
	v_mfma_f32_16x16x32_bf16 v[50:53], v[184:187], v[192:195], v[50:53]
	v_mfma_f32_16x16x32_bf16 v[50:53], v[188:191], v[196:199], v[50:53]
	v_mfma_f32_16x16x32_bf16 v[38:41], v[176:179], v[200:203], v[38:41]
	v_mfma_f32_16x16x32_bf16 v[38:41], v[180:183], v[204:207], v[38:41]
	v_mfma_f32_16x16x32_bf16 v[34:37], v[184:187], v[200:203], v[34:37]
	v_mfma_f32_16x16x32_bf16 v[34:37], v[188:191], v[204:207], v[34:37]
	v_mfma_f32_16x16x32_bf16 v[22:25], v[176:179], v[208:211], v[22:25]
	v_mfma_f32_16x16x32_bf16 v[22:25], v[180:183], v[212:215], v[22:25]
	v_mfma_f32_16x16x32_bf16 v[18:21], v[184:187], v[208:211], v[18:21]
	v_mfma_f32_16x16x32_bf16 v[18:21], v[188:191], v[212:215], v[18:21]
	v_mfma_f32_16x16x32_bf16 v[6:9], v[176:179], v[216:219], v[6:9]
	v_mfma_f32_16x16x32_bf16 v[6:9], v[180:183], v[220:223], v[6:9]
	v_mfma_f32_16x16x32_bf16 v[2:5], v[184:187], v[216:219], v[2:5]
	v_mfma_f32_16x16x32_bf16 v[2:5], v[188:191], v[220:223], v[2:5]
	s_barrier
	s_add_i32 s61, s61, 2
	s_add_u32 s28, s28, 0x8000
	s_addc_u32 s29, s29, 0
	s_add_u32 s59, s59, 0x8000
	s_addc_u32 s60, s60, 0
	s_cmp_gt_u32 s61, 61

.LBB0_1291:
	s_ashr_i32 s29, s28, 31
	s_lshl_b64 s[30:31], s[28:29], 23
	s_add_u32 s30, s84, s30
	s_addc_u32 s31, s85, s31
	s_and_b64 s[34:35], s[6:7], exec
	s_cselect_b32 s14, s31, s41
	s_cselect_b32 s29, s30, s40
	s_ashr_i32 s27, s26, 31
	s_lshl_b64 s[34:35], s[26:27], 23
	s_add_u32 s34, s51, s34
	v_readlane_b32 s27, v251, 62
	s_addc_u32 s35, s27, s35
	s_and_b64 s[44:45], s[6:7], exec
	s_cselect_b32 s27, s35, s43
	s_cselect_b32 s37, s34, s42
	s_add_u32 s40, s40, 0x404000
	s_addc_u32 s41, s41, 0
	s_add_u32 s39, s42, 0x8000
	s_addc_u32 s65, s43, 0
	s_mov_b32 s66, -2
	s_waitcnt lgkmcnt(0)
	ds_read_b128 v[130:133], v206
	ds_read_b128 v[134:137], v206 offset:1024
	ds_read_b128 v[138:141], v206 offset:2048
	ds_read_b128 v[142:145], v206 offset:3072
	ds_read_b128 v[146:149], v207
	ds_read_b128 v[150:153], v207 offset:1024
	ds_read_b128 v[176:179], v207 offset:2048
	ds_read_b128 v[180:183], v207 offset:3072
	s_add_u32 s42, s40, 0xffc04000
	s_addc_u32 s43, s41, -1
	s_cmpk_eq_i32 s66, 0xfc
	s_cselect_b32 s46, s29, s42
	s_cselect_b32 s47, s14, s43
	s_cselect_b32 s44, s37, s39
	s_cselect_b32 s45, s27, s65
	s_add_u32 s42, s46, 0x4000
	s_addc_u32 s43, s47, 0
	s_add_i32 m0, s53, 0xc000
	ds_read_b128 v[184:187], v208
	ds_read_b128 v[188:191], v208 offset:1024
	ds_read_b128 v[192:195], v208 offset:2048
	ds_read_b128 v[196:199], v208 offset:3072
	ds_read_b128 v[210:213], v208 offset:4096
	ds_read_b128 v[214:217], v208 offset:5120
	ds_read_b128 v[218:221], v208 offset:6144
	ds_read_b128 v[222:225], v208 offset:7168
	global_load_lds_dwordx4 v166, s[40:41]
	s_add_i32 m0, s53, 0xe000
	s_nop 0
	global_load_lds_dwordx4 v168, s[40:41]
	s_waitcnt vmcnt(24)
	s_waitcnt lgkmcnt(0)
	s_barrier
	s_waitcnt lgkmcnt(0)
	v_mfma_f32_16x16x32_bf16 v[126:129], v[130:133], v[184:187], 0
	v_mfma_f32_16x16x32_bf16 v[126:129], v[134:137], v[188:191], v[126:129]
	v_mfma_f32_16x16x32_bf16 v[122:125], v[138:141], v[184:187], 0
	v_mfma_f32_16x16x32_bf16 v[122:125], v[142:145], v[188:191], v[122:125]
	v_mfma_f32_16x16x32_bf16 v[110:113], v[130:133], v[192:195], 0
	v_mfma_f32_16x16x32_bf16 v[110:113], v[134:137], v[196:199], v[110:113]
	v_mfma_f32_16x16x32_bf16 v[106:109], v[138:141], v[192:195], 0
	v_mfma_f32_16x16x32_bf16 v[106:109], v[142:145], v[196:199], v[106:109]
	v_mfma_f32_16x16x32_bf16 v[94:97], v[130:133], v[210:213], 0
	v_mfma_f32_16x16x32_bf16 v[94:97], v[134:137], v[214:217], v[94:97]
	v_mfma_f32_16x16x32_bf16 v[90:93], v[138:141], v[210:213], 0
	v_mfma_f32_16x16x32_bf16 v[90:93], v[142:145], v[214:217], v[90:93]
	v_mfma_f32_16x16x32_bf16 v[78:81], v[130:133], v[218:221], 0
	v_mfma_f32_16x16x32_bf16 v[78:81], v[134:137], v[222:225], v[78:81]
	v_mfma_f32_16x16x32_bf16 v[74:77], v[138:141], v[218:221], 0
	v_mfma_f32_16x16x32_bf16 v[74:77], v[142:145], v[222:225], v[74:77]
	v_mfma_f32_16x16x32_bf16 v[118:121], v[146:149], v[184:187], 0
	v_mfma_f32_16x16x32_bf16 v[118:121], v[150:153], v[188:191], v[118:121]
	v_mfma_f32_16x16x32_bf16 v[114:117], v[176:179], v[184:187], 0
	v_mfma_f32_16x16x32_bf16 v[114:117], v[180:183], v[188:191], v[114:117]
	v_mfma_f32_16x16x32_bf16 v[102:105], v[146:149], v[192:195], 0
	v_mfma_f32_16x16x32_bf16 v[102:105], v[150:153], v[196:199], v[102:105]
	v_mfma_f32_16x16x32_bf16 v[98:101], v[176:179], v[192:195], 0
	v_mfma_f32_16x16x32_bf16 v[98:101], v[180:183], v[196:199], v[98:101]
	v_mfma_f32_16x16x32_bf16 v[86:89], v[146:149], v[210:213], 0
	v_mfma_f32_16x16x32_bf16 v[86:89], v[150:153], v[214:217], v[86:89]
	v_mfma_f32_16x16x32_bf16 v[82:85], v[176:179], v[210:213], 0
	v_mfma_f32_16x16x32_bf16 v[82:85], v[180:183], v[214:217], v[82:85]
	v_mfma_f32_16x16x32_bf16 v[70:73], v[146:149], v[218:221], 0
	v_mfma_f32_16x16x32_bf16 v[70:73], v[150:153], v[222:225], v[70:73]
	v_mfma_f32_16x16x32_bf16 v[66:69], v[176:179], v[218:221], 0
	v_mfma_f32_16x16x32_bf16 v[66:69], v[180:183], v[222:225], v[66:69]
	s_barrier
	s_add_i32 s67, s62, s52
	s_mov_b32 m0, s67
	ds_read_b128 v[184:187], v208 offset:16384
	ds_read_b128 v[188:191], v208 offset:17408
	ds_read_b128 v[192:195], v208 offset:18432
	ds_read_b128 v[196:199], v208 offset:19456
	ds_read_b128 v[210:213], v208 offset:20480
	ds_read_b128 v[214:217], v208 offset:21504
	ds_read_b128 v[218:221], v208 offset:22528
	ds_read_b128 v[222:225], v208 offset:23552
	global_load_lds_dwordx4 v156, s[44:45]
	s_add_i32 m0, s67, 0x2000
	s_add_u32 s68, s44, 0x400000
	s_addc_u32 s69, s45, 0
	s_add_i32 s67, s63, s52
	global_load_lds_dwordx4 v160, s[44:45]
	s_mov_b32 m0, s67
	s_nop 0
	global_load_lds_dwordx4 v156, s[68:69]
	s_add_i32 m0, s67, 0x2000
	s_nop 0
	global_load_lds_dwordx4 v160, s[68:69]
	s_mov_b32 m0, s53
	s_nop 0
	global_load_lds_dwordx4 v154, s[46:47]
	s_mov_b32 m0, s54
	s_nop 0
	global_load_lds_dwordx4 v158, s[46:47]
	s_waitcnt vmcnt(8)
	s_waitcnt lgkmcnt(0)
	s_barrier
	s_waitcnt lgkmcnt(0)
	v_mfma_f32_16x16x32_bf16 v[62:65], v[130:133], v[184:187], 0
	v_mfma_f32_16x16x32_bf16 v[62:65], v[134:137], v[188:191], v[62:65]
	v_mfma_f32_16x16x32_bf16 v[58:61], v[138:141], v[184:187], 0
	v_mfma_f32_16x16x32_bf16 v[58:61], v[142:145], v[188:191], v[58:61]
	v_mfma_f32_16x16x32_bf16 v[46:49], v[130:133], v[192:195], 0
	v_mfma_f32_16x16x32_bf16 v[46:49], v[134:137], v[196:199], v[46:49]
	v_mfma_f32_16x16x32_bf16 v[42:45], v[138:141], v[192:195], 0
	v_mfma_f32_16x16x32_bf16 v[42:45], v[142:145], v[196:199], v[42:45]
	v_mfma_f32_16x16x32_bf16 v[30:33], v[130:133], v[210:213], 0
	v_mfma_f32_16x16x32_bf16 v[30:33], v[134:137], v[214:217], v[30:33]
	v_mfma_f32_16x16x32_bf16 v[26:29], v[138:141], v[210:213], 0
	v_mfma_f32_16x16x32_bf16 v[26:29], v[142:145], v[214:217], v[26:29]
	v_mfma_f32_16x16x32_bf16 v[14:17], v[130:133], v[218:221], 0
	v_mfma_f32_16x16x32_bf16 v[14:17], v[134:137], v[222:225], v[14:17]
	v_mfma_f32_16x16x32_bf16 v[10:13], v[138:141], v[218:221], 0
	v_mfma_f32_16x16x32_bf16 v[10:13], v[142:145], v[222:225], v[10:13]
	v_mfma_f32_16x16x32_bf16 v[54:57], v[146:149], v[184:187], 0
	v_mfma_f32_16x16x32_bf16 v[54:57], v[150:153], v[188:191], v[54:57]
	v_mfma_f32_16x16x32_bf16 v[50:53], v[176:179], v[184:187], 0
	v_mfma_f32_16x16x32_bf16 v[50:53], v[180:183], v[188:191], v[50:53]
	v_mfma_f32_16x16x32_bf16 v[38:41], v[146:149], v[192:195], 0
	v_mfma_f32_16x16x32_bf16 v[38:41], v[150:153], v[196:199], v[38:41]
	v_mfma_f32_16x16x32_bf16 v[34:37], v[176:179], v[192:195], 0
	v_mfma_f32_16x16x32_bf16 v[34:37], v[180:183], v[196:199], v[34:37]
	v_mfma_f32_16x16x32_bf16 v[22:25], v[146:149], v[210:213], 0
	v_mfma_f32_16x16x32_bf16 v[22:25], v[150:153], v[214:217], v[22:25]
	v_mfma_f32_16x16x32_bf16 v[18:21], v[176:179], v[210:213], 0
	v_mfma_f32_16x16x32_bf16 v[18:21], v[180:183], v[214:217], v[18:21]
	v_mfma_f32_16x16x32_bf16 v[6:9], v[146:149], v[218:221], 0
	v_mfma_f32_16x16x32_bf16 v[6:9], v[150:153], v[222:225], v[6:9]
	v_mfma_f32_16x16x32_bf16 v[2:5], v[176:179], v[218:221], 0
	v_mfma_f32_16x16x32_bf16 v[2:5], v[180:183], v[222:225], v[2:5]
	s_barrier
	s_add_i32 s67, 0, 0x18000
	s_add_i32 s68, 0, 0x1c000
	v_add_u32_e32 v142, s67, v203
	v_add_u32_e32 v162, s68, v203
	ds_read_b128 v[130:133], v142
	ds_read_b128 v[134:137], v142 offset:1024
	ds_read_b128 v[138:141], v142 offset:2048
	ds_read_b128 v[142:145], v142 offset:3072
	ds_read_b128 v[146:149], v162
	ds_read_b128 v[150:153], v162 offset:1024
	ds_read_b128 v[176:179], v162 offset:2048
	ds_read_b128 v[180:183], v162 offset:3072
	s_add_u32 s46, s46, 0x400000
	s_addc_u32 s47, s47, 0
	s_mov_b32 m0, s55
	ds_read_b128 v[184:187], v208 offset:32768
	ds_read_b128 v[188:191], v208 offset:33792
	ds_read_b128 v[192:195], v208 offset:34816
	ds_read_b128 v[196:199], v208 offset:35840
	ds_read_b128 v[210:213], v208 offset:36864
	ds_read_b128 v[214:217], v208 offset:37888
	ds_read_b128 v[218:221], v208 offset:38912
	ds_read_b128 v[222:225], v208 offset:39936
	global_load_lds_dwordx4 v154, s[46:47]
	s_mov_b32 m0, s56
	s_nop 0
	global_load_lds_dwordx4 v158, s[46:47]
	s_waitcnt vmcnt(8)
	s_waitcnt lgkmcnt(0)
	s_barrier
	s_waitcnt lgkmcnt(0)
	v_mfma_f32_16x16x32_bf16 v[126:129], v[130:133], v[184:187], v[126:129]
	v_mfma_f32_16x16x32_bf16 v[126:129], v[134:137], v[188:191], v[126:129]
	v_mfma_f32_16x16x32_bf16 v[122:125], v[138:141], v[184:187], v[122:125]
	v_mfma_f32_16x16x32_bf16 v[122:125], v[142:145], v[188:191], v[122:125]
	v_mfma_f32_16x16x32_bf16 v[110:113], v[130:133], v[192:195], v[110:113]
	v_mfma_f32_16x16x32_bf16 v[110:113], v[134:137], v[196:199], v[110:113]
	v_mfma_f32_16x16x32_bf16 v[106:109], v[138:141], v[192:195], v[106:109]
	v_mfma_f32_16x16x32_bf16 v[106:109], v[142:145], v[196:199], v[106:109]
	v_mfma_f32_16x16x32_bf16 v[94:97], v[130:133], v[210:213], v[94:97]
	v_mfma_f32_16x16x32_bf16 v[94:97], v[134:137], v[214:217], v[94:97]
	v_mfma_f32_16x16x32_bf16 v[90:93], v[138:141], v[210:213], v[90:93]
	v_mfma_f32_16x16x32_bf16 v[90:93], v[142:145], v[214:217], v[90:93]
	v_mfma_f32_16x16x32_bf16 v[78:81], v[130:133], v[218:221], v[78:81]
	v_mfma_f32_16x16x32_bf16 v[78:81], v[134:137], v[222:225], v[78:81]
	v_mfma_f32_16x16x32_bf16 v[74:77], v[138:141], v[218:221], v[74:77]
	v_mfma_f32_16x16x32_bf16 v[74:77], v[142:145], v[222:225], v[74:77]
	v_mfma_f32_16x16x32_bf16 v[118:121], v[146:149], v[184:187], v[118:121]
	v_mfma_f32_16x16x32_bf16 v[118:121], v[150:153], v[188:191], v[118:121]
	v_mfma_f32_16x16x32_bf16 v[114:117], v[176:179], v[184:187], v[114:117]
	v_mfma_f32_16x16x32_bf16 v[114:117], v[180:183], v[188:191], v[114:117]
	v_mfma_f32_16x16x32_bf16 v[102:105], v[146:149], v[192:195], v[102:105]
	v_mfma_f32_16x16x32_bf16 v[102:105], v[150:153], v[196:199], v[102:105]
	v_mfma_f32_16x16x32_bf16 v[98:101], v[176:179], v[192:195], v[98:101]
	v_mfma_f32_16x16x32_bf16 v[98:101], v[180:183], v[196:199], v[98:101]
	v_mfma_f32_16x16x32_bf16 v[86:89], v[146:149], v[210:213], v[86:89]
	v_mfma_f32_16x16x32_bf16 v[86:89], v[150:153], v[214:217], v[86:89]
	v_mfma_f32_16x16x32_bf16 v[82:85], v[176:179], v[210:213], v[82:85]
	v_mfma_f32_16x16x32_bf16 v[82:85], v[180:183], v[214:217], v[82:85]
	v_mfma_f32_16x16x32_bf16 v[70:73], v[146:149], v[218:221], v[70:73]
	v_mfma_f32_16x16x32_bf16 v[70:73], v[150:153], v[222:225], v[70:73]
	v_mfma_f32_16x16x32_bf16 v[66:69], v[176:179], v[218:221], v[66:69]
	v_mfma_f32_16x16x32_bf16 v[66:69], v[180:183], v[222:225], v[66:69]
	s_barrier
	s_add_u32 s46, s44, 0x4000
	s_addc_u32 s47, s45, 0
	s_add_i32 s67, s67, s52
	s_mov_b32 m0, s67
	ds_read_b128 v[184:187], v208 offset:49152
	ds_read_b128 v[188:191], v208 offset:50176
	ds_read_b128 v[192:195], v208 offset:51200
	ds_read_b128 v[196:199], v208 offset:52224
	ds_read_b128 v[210:213], v208 offset:53248
	ds_read_b128 v[214:217], v208 offset:54272
	ds_read_b128 v[218:221], v208 offset:55296
	ds_read_b128 v[222:225], v208 offset:56320
	global_load_lds_dwordx4 v156, s[46:47]
	s_add_i32 m0, s67, 0x2000
	s_add_u32 s44, s44, 0x404000
	s_addc_u32 s45, s45, 0
	global_load_lds_dwordx4 v160, s[46:47]
	s_add_i32 s46, s68, s52
	s_mov_b32 m0, s46
	s_nop 0
	global_load_lds_dwordx4 v156, s[44:45]
	s_add_i32 m0, s46, 0x2000
	s_nop 0
	global_load_lds_dwordx4 v160, s[44:45]
	s_mov_b32 m0, s60
	s_nop 0
	global_load_lds_dwordx4 v154, s[42:43]
	s_mov_b32 m0, s61
	s_nop 0
	global_load_lds_dwordx4 v158, s[42:43]
	s_waitcnt vmcnt(8)
	s_waitcnt lgkmcnt(0)
	s_barrier
	s_waitcnt lgkmcnt(0)
	v_mfma_f32_16x16x32_bf16 v[62:65], v[130:133], v[184:187], v[62:65]
	v_mfma_f32_16x16x32_bf16 v[62:65], v[134:137], v[188:191], v[62:65]
	v_mfma_f32_16x16x32_bf16 v[58:61], v[138:141], v[184:187], v[58:61]
	v_mfma_f32_16x16x32_bf16 v[58:61], v[142:145], v[188:191], v[58:61]
	v_mfma_f32_16x16x32_bf16 v[46:49], v[130:133], v[192:195], v[46:49]
	v_mfma_f32_16x16x32_bf16 v[46:49], v[134:137], v[196:199], v[46:49]
	v_mfma_f32_16x16x32_bf16 v[42:45], v[138:141], v[192:195], v[42:45]
	v_mfma_f32_16x16x32_bf16 v[42:45], v[142:145], v[196:199], v[42:45]
	v_mfma_f32_16x16x32_bf16 v[30:33], v[130:133], v[210:213], v[30:33]
	v_mfma_f32_16x16x32_bf16 v[30:33], v[134:137], v[214:217], v[30:33]
	v_mfma_f32_16x16x32_bf16 v[26:29], v[138:141], v[210:213], v[26:29]
	v_mfma_f32_16x16x32_bf16 v[26:29], v[142:145], v[214:217], v[26:29]
	v_mfma_f32_16x16x32_bf16 v[14:17], v[130:133], v[218:221], v[14:17]
	v_mfma_f32_16x16x32_bf16 v[14:17], v[134:137], v[222:225], v[14:17]
	v_mfma_f32_16x16x32_bf16 v[10:13], v[138:141], v[218:221], v[10:13]
	v_mfma_f32_16x16x32_bf16 v[10:13], v[142:145], v[222:225], v[10:13]
	v_mfma_f32_16x16x32_bf16 v[54:57], v[146:149], v[184:187], v[54:57]
	v_mfma_f32_16x16x32_bf16 v[54:57], v[150:153], v[188:191], v[54:57]
	v_mfma_f32_16x16x32_bf16 v[50:53], v[176:179], v[184:187], v[50:53]
	v_mfma_f32_16x16x32_bf16 v[50:53], v[180:183], v[188:191], v[50:53]
	v_mfma_f32_16x16x32_bf16 v[38:41], v[146:149], v[192:195], v[38:41]
	v_mfma_f32_16x16x32_bf16 v[38:41], v[150:153], v[196:199], v[38:41]
	v_mfma_f32_16x16x32_bf16 v[34:37], v[176:179], v[192:195], v[34:37]
	v_mfma_f32_16x16x32_bf16 v[34:37], v[180:183], v[196:199], v[34:37]
	v_mfma_f32_16x16x32_bf16 v[22:25], v[146:149], v[210:213], v[22:25]
	v_mfma_f32_16x16x32_bf16 v[22:25], v[150:153], v[214:217], v[22:25]
	v_mfma_f32_16x16x32_bf16 v[18:21], v[176:179], v[210:213], v[18:21]
	v_mfma_f32_16x16x32_bf16 v[18:21], v[180:183], v[214:217], v[18:21]
	v_mfma_f32_16x16x32_bf16 v[6:9], v[146:149], v[218:221], v[6:9]
	v_mfma_f32_16x16x32_bf16 v[6:9], v[150:153], v[222:225], v[6:9]
	v_mfma_f32_16x16x32_bf16 v[2:5], v[176:179], v[218:221], v[2:5]
	v_mfma_f32_16x16x32_bf16 v[2:5], v[180:183], v[222:225], v[2:5]
	s_barrier
	s_add_i32 s66, s66, 2
	s_add_u32 s40, s40, 0x8000
	s_addc_u32 s41, s41, 0
	s_add_u32 s39, s39, 0x8000
	s_addc_u32 s65, s65, 0
	s_cmpk_gt_u32 s66, 0xfd

.LBB0_1386:
	s_ashr_i32 s21, s20, 31
	s_lshl_b64 s[22:23], s[20:21], 21
	s_add_u32 s22, s0, s22
	s_addc_u32 s23, s1, s23
	s_and_b64 s[24:25], s[2:3], exec
	s_cselect_b32 s21, s23, s31
	s_cselect_b32 s27, s22, s30
	s_ashr_i32 s19, s18, 31
	s_lshl_b64 s[24:25], s[18:19], 21
	s_add_u32 s24, s48, s24
	s_addc_u32 s25, s49, s25
	s_and_b64 s[36:37], s[2:3], exec
	s_cselect_b32 s19, s25, s35
	s_cselect_b32 s29, s24, s34
	s_add_u32 s30, s30, 0x104000
	s_addc_u32 s31, s31, 0
	s_add_u32 s52, s34, 0x8000
	s_addc_u32 s53, s35, 0
	s_mov_b32 s54, -2
	ds_read_b128 v[62:65], v189
	ds_read_b128 v[66:69], v189 offset:1024
	ds_read_b128 v[74:77], v189 offset:2048
	ds_read_b128 v[78:81], v189 offset:3072
	ds_read_b128 v[146:149], v195
	ds_read_b128 v[150:153], v195 offset:1024
	ds_read_b128 v[154:157], v195 offset:2048
	ds_read_b128 v[158:161], v195 offset:3072
	s_add_u32 s34, s30, 0xfff04000
	s_addc_u32 s35, s31, -1
	s_cmp_eq_u32 s54, 60
	s_cselect_b32 s38, s27, s34
	s_cselect_b32 s39, s21, s35
	s_cselect_b32 s36, s29, s52
	s_cselect_b32 s37, s19, s53
	s_add_u32 s34, s38, 0x4000
	s_addc_u32 s35, s39, 0
	s_add_i32 m0, s40, 0xc000
	ds_read_b128 v[190:193], v197
	ds_read_b128 v[198:201], v197 offset:1024
	ds_read_b128 v[202:205], v197 offset:2048
	ds_read_b128 v[206:209], v197 offset:3072
	ds_read_b128 v[210:213], v197 offset:4096
	ds_read_b128 v[214:217], v197 offset:5120
	ds_read_b128 v[218:221], v197 offset:6144
	ds_read_b128 v[222:225], v197 offset:7168
	global_load_lds_dwordx4 v172, s[30:31]
	s_add_i32 m0, s40, 0xe000
	s_nop 0
	global_load_lds_dwordx4 v174, s[30:31]
	s_waitcnt vmcnt(24)
	s_waitcnt lgkmcnt(0)
	s_barrier
	s_waitcnt lgkmcnt(0)
	v_mfma_f32_16x16x32_bf16 v[142:145], v[62:65], v[190:193], 0
	v_mfma_f32_16x16x32_bf16 v[142:145], v[66:69], v[198:201], v[142:145]
	v_mfma_f32_16x16x32_bf16 v[138:141], v[74:77], v[190:193], 0
	v_mfma_f32_16x16x32_bf16 v[138:141], v[78:81], v[198:201], v[138:141]
	v_mfma_f32_16x16x32_bf16 v[126:129], v[62:65], v[202:205], 0
	v_mfma_f32_16x16x32_bf16 v[126:129], v[66:69], v[206:209], v[126:129]
	v_mfma_f32_16x16x32_bf16 v[122:125], v[74:77], v[202:205], 0
	v_mfma_f32_16x16x32_bf16 v[122:125], v[78:81], v[206:209], v[122:125]
	v_mfma_f32_16x16x32_bf16 v[110:113], v[62:65], v[210:213], 0
	v_mfma_f32_16x16x32_bf16 v[110:113], v[66:69], v[214:217], v[110:113]
	v_mfma_f32_16x16x32_bf16 v[106:109], v[74:77], v[210:213], 0
	v_mfma_f32_16x16x32_bf16 v[106:109], v[78:81], v[214:217], v[106:109]
	v_mfma_f32_16x16x32_bf16 v[94:97], v[62:65], v[218:221], 0
	v_mfma_f32_16x16x32_bf16 v[94:97], v[66:69], v[222:225], v[94:97]
	v_mfma_f32_16x16x32_bf16 v[90:93], v[74:77], v[218:221], 0
	v_mfma_f32_16x16x32_bf16 v[90:93], v[78:81], v[222:225], v[90:93]
	v_mfma_f32_16x16x32_bf16 v[134:137], v[146:149], v[190:193], 0
	v_mfma_f32_16x16x32_bf16 v[134:137], v[150:153], v[198:201], v[134:137]
	v_mfma_f32_16x16x32_bf16 v[130:133], v[154:157], v[190:193], 0
	v_mfma_f32_16x16x32_bf16 v[130:133], v[158:161], v[198:201], v[130:133]
	v_mfma_f32_16x16x32_bf16 v[118:121], v[146:149], v[202:205], 0
	v_mfma_f32_16x16x32_bf16 v[118:121], v[150:153], v[206:209], v[118:121]
	v_mfma_f32_16x16x32_bf16 v[114:117], v[154:157], v[202:205], 0
	v_mfma_f32_16x16x32_bf16 v[114:117], v[158:161], v[206:209], v[114:117]
	v_mfma_f32_16x16x32_bf16 v[102:105], v[146:149], v[210:213], 0
	v_mfma_f32_16x16x32_bf16 v[102:105], v[150:153], v[214:217], v[102:105]
	v_mfma_f32_16x16x32_bf16 v[98:101], v[154:157], v[210:213], 0
	v_mfma_f32_16x16x32_bf16 v[98:101], v[158:161], v[214:217], v[98:101]
	v_mfma_f32_16x16x32_bf16 v[86:89], v[146:149], v[218:221], 0
	v_mfma_f32_16x16x32_bf16 v[86:89], v[150:153], v[222:225], v[86:89]
	v_mfma_f32_16x16x32_bf16 v[82:85], v[154:157], v[218:221], 0
	v_mfma_f32_16x16x32_bf16 v[82:85], v[158:161], v[222:225], v[82:85]
	s_barrier
	s_add_i32 s55, s50, s33
	s_mov_b32 m0, s55
	ds_read_b128 v[190:193], v197 offset:16384
	ds_read_b128 v[198:201], v197 offset:17408
	ds_read_b128 v[202:205], v197 offset:18432
	ds_read_b128 v[206:209], v197 offset:19456
	ds_read_b128 v[210:213], v197 offset:20480
	ds_read_b128 v[214:217], v197 offset:21504
	ds_read_b128 v[218:221], v197 offset:22528
	ds_read_b128 v[222:225], v197 offset:23552
	global_load_lds_dwordx4 v166, s[36:37]
	s_add_i32 m0, s55, 0x2000
	s_add_u32 s56, s36, 0x100000
	s_addc_u32 s57, s37, 0
	s_add_i32 s55, s51, s33
	global_load_lds_dwordx4 v162, s[36:37]
	s_mov_b32 m0, s55
	s_nop 0
	global_load_lds_dwordx4 v166, s[56:57]
	s_add_i32 m0, s55, 0x2000
	s_nop 0
	global_load_lds_dwordx4 v162, s[56:57]
	s_mov_b32 m0, s40
	s_nop 0
	global_load_lds_dwordx4 v168, s[38:39]
	s_mov_b32 m0, s41
	s_nop 0
	global_load_lds_dwordx4 v164, s[38:39]
	s_waitcnt vmcnt(8)
	s_waitcnt lgkmcnt(0)
	s_barrier
	s_waitcnt lgkmcnt(0)
	v_mfma_f32_16x16x32_bf16 v[70:73], v[62:65], v[190:193], 0
	v_mfma_f32_16x16x32_bf16 v[70:73], v[66:69], v[198:201], v[70:73]
	v_mfma_f32_16x16x32_bf16 v[58:61], v[74:77], v[190:193], 0
	v_mfma_f32_16x16x32_bf16 v[58:61], v[78:81], v[198:201], v[58:61]
	v_mfma_f32_16x16x32_bf16 v[46:49], v[62:65], v[202:205], 0
	v_mfma_f32_16x16x32_bf16 v[46:49], v[66:69], v[206:209], v[46:49]
	v_mfma_f32_16x16x32_bf16 v[42:45], v[74:77], v[202:205], 0
	v_mfma_f32_16x16x32_bf16 v[42:45], v[78:81], v[206:209], v[42:45]
	v_mfma_f32_16x16x32_bf16 v[30:33], v[62:65], v[210:213], 0
	v_mfma_f32_16x16x32_bf16 v[30:33], v[66:69], v[214:217], v[30:33]
	v_mfma_f32_16x16x32_bf16 v[26:29], v[74:77], v[210:213], 0
	v_mfma_f32_16x16x32_bf16 v[26:29], v[78:81], v[214:217], v[26:29]
	v_mfma_f32_16x16x32_bf16 v[14:17], v[62:65], v[218:221], 0
	v_mfma_f32_16x16x32_bf16 v[14:17], v[66:69], v[222:225], v[14:17]
	v_mfma_f32_16x16x32_bf16 v[10:13], v[74:77], v[218:221], 0
	v_mfma_f32_16x16x32_bf16 v[10:13], v[78:81], v[222:225], v[10:13]
	v_mfma_f32_16x16x32_bf16 v[54:57], v[146:149], v[190:193], 0
	v_mfma_f32_16x16x32_bf16 v[54:57], v[150:153], v[198:201], v[54:57]
	v_mfma_f32_16x16x32_bf16 v[50:53], v[154:157], v[190:193], 0
	v_mfma_f32_16x16x32_bf16 v[50:53], v[158:161], v[198:201], v[50:53]
	v_mfma_f32_16x16x32_bf16 v[38:41], v[146:149], v[202:205], 0
	v_mfma_f32_16x16x32_bf16 v[38:41], v[150:153], v[206:209], v[38:41]
	v_mfma_f32_16x16x32_bf16 v[34:37], v[154:157], v[202:205], 0
	v_mfma_f32_16x16x32_bf16 v[34:37], v[158:161], v[206:209], v[34:37]
	v_mfma_f32_16x16x32_bf16 v[22:25], v[146:149], v[210:213], 0
	v_mfma_f32_16x16x32_bf16 v[22:25], v[150:153], v[214:217], v[22:25]
	v_mfma_f32_16x16x32_bf16 v[18:21], v[154:157], v[210:213], 0
	v_mfma_f32_16x16x32_bf16 v[18:21], v[158:161], v[214:217], v[18:21]
	v_mfma_f32_16x16x32_bf16 v[6:9], v[146:149], v[218:221], 0
	v_mfma_f32_16x16x32_bf16 v[6:9], v[150:153], v[222:225], v[6:9]
	v_mfma_f32_16x16x32_bf16 v[2:5], v[154:157], v[218:221], 0
	v_mfma_f32_16x16x32_bf16 v[2:5], v[158:161], v[222:225], v[2:5]
	s_barrier
	s_add_i32 s55, 0, 0x18000
	s_add_i32 s56, 0, 0x1c000
	v_add_u32_e32 v78, s55, v187
	v_add_u32_e32 v158, s56, v187
	ds_read_b128 v[62:65], v78
	ds_read_b128 v[66:69], v78 offset:1024
	ds_read_b128 v[74:77], v78 offset:2048
	ds_read_b128 v[78:81], v78 offset:3072
	ds_read_b128 v[146:149], v158
	ds_read_b128 v[150:153], v158 offset:1024
	ds_read_b128 v[154:157], v158 offset:2048
	ds_read_b128 v[158:161], v158 offset:3072
	s_add_u32 s38, s38, 0x100000
	s_addc_u32 s39, s39, 0
	s_mov_b32 m0, s42
	ds_read_b128 v[190:193], v197 offset:32768
	ds_read_b128 v[198:201], v197 offset:33792
	ds_read_b128 v[202:205], v197 offset:34816
	ds_read_b128 v[206:209], v197 offset:35840
	ds_read_b128 v[210:213], v197 offset:36864
	ds_read_b128 v[214:217], v197 offset:37888
	ds_read_b128 v[218:221], v197 offset:38912
	ds_read_b128 v[222:225], v197 offset:39936
	global_load_lds_dwordx4 v168, s[38:39]
	s_mov_b32 m0, s43
	s_nop 0
	global_load_lds_dwordx4 v164, s[38:39]
	s_waitcnt vmcnt(8)
	s_waitcnt lgkmcnt(0)
	s_barrier
	s_waitcnt lgkmcnt(0)
	v_mfma_f32_16x16x32_bf16 v[142:145], v[62:65], v[190:193], v[142:145]
	v_mfma_f32_16x16x32_bf16 v[142:145], v[66:69], v[198:201], v[142:145]
	v_mfma_f32_16x16x32_bf16 v[138:141], v[74:77], v[190:193], v[138:141]
	v_mfma_f32_16x16x32_bf16 v[138:141], v[78:81], v[198:201], v[138:141]
	v_mfma_f32_16x16x32_bf16 v[126:129], v[62:65], v[202:205], v[126:129]
	v_mfma_f32_16x16x32_bf16 v[126:129], v[66:69], v[206:209], v[126:129]
	v_mfma_f32_16x16x32_bf16 v[122:125], v[74:77], v[202:205], v[122:125]
	v_mfma_f32_16x16x32_bf16 v[122:125], v[78:81], v[206:209], v[122:125]
	v_mfma_f32_16x16x32_bf16 v[110:113], v[62:65], v[210:213], v[110:113]
	v_mfma_f32_16x16x32_bf16 v[110:113], v[66:69], v[214:217], v[110:113]
	v_mfma_f32_16x16x32_bf16 v[106:109], v[74:77], v[210:213], v[106:109]
	v_mfma_f32_16x16x32_bf16 v[106:109], v[78:81], v[214:217], v[106:109]
	v_mfma_f32_16x16x32_bf16 v[94:97], v[62:65], v[218:221], v[94:97]
	v_mfma_f32_16x16x32_bf16 v[94:97], v[66:69], v[222:225], v[94:97]
	v_mfma_f32_16x16x32_bf16 v[90:93], v[74:77], v[218:221], v[90:93]
	v_mfma_f32_16x16x32_bf16 v[90:93], v[78:81], v[222:225], v[90:93]
	v_mfma_f32_16x16x32_bf16 v[134:137], v[146:149], v[190:193], v[134:137]
	v_mfma_f32_16x16x32_bf16 v[134:137], v[150:153], v[198:201], v[134:137]
	v_mfma_f32_16x16x32_bf16 v[130:133], v[154:157], v[190:193], v[130:133]
	v_mfma_f32_16x16x32_bf16 v[130:133], v[158:161], v[198:201], v[130:133]
	v_mfma_f32_16x16x32_bf16 v[118:121], v[146:149], v[202:205], v[118:121]
	v_mfma_f32_16x16x32_bf16 v[118:121], v[150:153], v[206:209], v[118:121]
	v_mfma_f32_16x16x32_bf16 v[114:117], v[154:157], v[202:205], v[114:117]
	v_mfma_f32_16x16x32_bf16 v[114:117], v[158:161], v[206:209], v[114:117]
	v_mfma_f32_16x16x32_bf16 v[102:105], v[146:149], v[210:213], v[102:105]
	v_mfma_f32_16x16x32_bf16 v[102:105], v[150:153], v[214:217], v[102:105]
	v_mfma_f32_16x16x32_bf16 v[98:101], v[154:157], v[210:213], v[98:101]
	v_mfma_f32_16x16x32_bf16 v[98:101], v[158:161], v[214:217], v[98:101]
	v_mfma_f32_16x16x32_bf16 v[86:89], v[146:149], v[218:221], v[86:89]
	v_mfma_f32_16x16x32_bf16 v[86:89], v[150:153], v[222:225], v[86:89]
	v_mfma_f32_16x16x32_bf16 v[82:85], v[154:157], v[218:221], v[82:85]
	v_mfma_f32_16x16x32_bf16 v[82:85], v[158:161], v[222:225], v[82:85]
	s_barrier
	s_add_u32 s38, s36, 0x4000
	s_addc_u32 s39, s37, 0
	s_add_i32 s55, s55, s33
	s_mov_b32 m0, s55
	ds_read_b128 v[190:193], v197 offset:49152
	ds_read_b128 v[198:201], v197 offset:50176
	ds_read_b128 v[202:205], v197 offset:51200
	ds_read_b128 v[206:209], v197 offset:52224
	ds_read_b128 v[210:213], v197 offset:53248
	ds_read_b128 v[214:217], v197 offset:54272
	ds_read_b128 v[218:221], v197 offset:55296
	ds_read_b128 v[222:225], v197 offset:56320
	global_load_lds_dwordx4 v166, s[38:39]
	s_add_i32 m0, s55, 0x2000
	s_add_u32 s36, s36, 0x104000
	s_addc_u32 s37, s37, 0
	global_load_lds_dwordx4 v162, s[38:39]
	s_add_i32 s38, s56, s33
	s_mov_b32 m0, s38
	s_nop 0
	global_load_lds_dwordx4 v166, s[36:37]
	s_add_i32 m0, s38, 0x2000
	s_nop 0
	global_load_lds_dwordx4 v162, s[36:37]
	s_mov_b32 m0, s46
	s_nop 0
	global_load_lds_dwordx4 v168, s[34:35]
	s_mov_b32 m0, s47
	s_nop 0
	global_load_lds_dwordx4 v164, s[34:35]
	s_waitcnt vmcnt(8)
	s_waitcnt lgkmcnt(0)
	s_barrier
	s_waitcnt lgkmcnt(0)
	v_mfma_f32_16x16x32_bf16 v[70:73], v[62:65], v[190:193], v[70:73]
	v_mfma_f32_16x16x32_bf16 v[70:73], v[66:69], v[198:201], v[70:73]
	v_mfma_f32_16x16x32_bf16 v[58:61], v[74:77], v[190:193], v[58:61]
	v_mfma_f32_16x16x32_bf16 v[58:61], v[78:81], v[198:201], v[58:61]
	v_mfma_f32_16x16x32_bf16 v[46:49], v[62:65], v[202:205], v[46:49]
	v_mfma_f32_16x16x32_bf16 v[46:49], v[66:69], v[206:209], v[46:49]
	v_mfma_f32_16x16x32_bf16 v[42:45], v[74:77], v[202:205], v[42:45]
	v_mfma_f32_16x16x32_bf16 v[42:45], v[78:81], v[206:209], v[42:45]
	v_mfma_f32_16x16x32_bf16 v[30:33], v[62:65], v[210:213], v[30:33]
	v_mfma_f32_16x16x32_bf16 v[30:33], v[66:69], v[214:217], v[30:33]
	v_mfma_f32_16x16x32_bf16 v[26:29], v[74:77], v[210:213], v[26:29]
	v_mfma_f32_16x16x32_bf16 v[26:29], v[78:81], v[214:217], v[26:29]
	v_mfma_f32_16x16x32_bf16 v[14:17], v[62:65], v[218:221], v[14:17]
	v_mfma_f32_16x16x32_bf16 v[14:17], v[66:69], v[222:225], v[14:17]
	v_mfma_f32_16x16x32_bf16 v[10:13], v[74:77], v[218:221], v[10:13]
	v_mfma_f32_16x16x32_bf16 v[10:13], v[78:81], v[222:225], v[10:13]
	v_mfma_f32_16x16x32_bf16 v[54:57], v[146:149], v[190:193], v[54:57]
	v_mfma_f32_16x16x32_bf16 v[54:57], v[150:153], v[198:201], v[54:57]
	v_mfma_f32_16x16x32_bf16 v[50:53], v[154:157], v[190:193], v[50:53]
	v_mfma_f32_16x16x32_bf16 v[50:53], v[158:161], v[198:201], v[50:53]
	v_mfma_f32_16x16x32_bf16 v[38:41], v[146:149], v[202:205], v[38:41]
	v_mfma_f32_16x16x32_bf16 v[38:41], v[150:153], v[206:209], v[38:41]
	v_mfma_f32_16x16x32_bf16 v[34:37], v[154:157], v[202:205], v[34:37]
	v_mfma_f32_16x16x32_bf16 v[34:37], v[158:161], v[206:209], v[34:37]
	v_mfma_f32_16x16x32_bf16 v[22:25], v[146:149], v[210:213], v[22:25]
	v_mfma_f32_16x16x32_bf16 v[22:25], v[150:153], v[214:217], v[22:25]
	v_mfma_f32_16x16x32_bf16 v[18:21], v[154:157], v[210:213], v[18:21]
	v_mfma_f32_16x16x32_bf16 v[18:21], v[158:161], v[214:217], v[18:21]
	v_mfma_f32_16x16x32_bf16 v[6:9], v[146:149], v[218:221], v[6:9]
	v_mfma_f32_16x16x32_bf16 v[6:9], v[150:153], v[222:225], v[6:9]
	v_mfma_f32_16x16x32_bf16 v[2:5], v[154:157], v[218:221], v[2:5]
	v_mfma_f32_16x16x32_bf16 v[2:5], v[158:161], v[222:225], v[2:5]
	s_barrier
	s_add_i32 s54, s54, 2
	s_add_u32 s30, s30, 0x8000
	s_addc_u32 s31, s31, 0
	s_add_u32 s52, s52, 0x8000
	s_addc_u32 s53, s53, 0
	s_cmp_gt_u32 s54, 61
